# GEMM K-loops: redundant s_waitcnt lgkmcnt(0) right after the barrier (same wait sits right before it) removed; compute segments are bare MFMAs
# baseline (speedup 1.0000x reference)
; #define PG8_STAGE(bufoff, gbase, voff) do { _Pragma("unroll") for (int _i = 0; _i < 2; ++_i) \
;         __builtin_amdgcn_global_load_lds((const unsigned*)((const char*)(gbase) + (voff)[_i]), (PG8_LAS unsigned*)(lds + (bufoff) + ldsw + _i * 8192), 16, 0, 0); } while (0)
; #define PG8_LDA(dst, b, h) do { _Pragma("unroll") for (int m = 0; m < 4; ++m) _Pragma("unroll") for (int k = 0; k < 2; ++k) dst[m][k] = *(const PG8_LAS bf16x8*)(lds + PG8_SA(b, h) + aoff + m * 2048 + k * 1024); } while (0)
; #define PG8_LDB(dst, b, h) do { _Pragma("unroll") for (int n = 0; n < 2; ++n) _Pragma("unroll") for (int k = 0; k < 2; ++k) dst[n][k] = *(const PG8_LAS bf16x8*)(lds + PG8_SB(b, h) + boff + n * 2048 + k * 1024); } while (0)
; #define PG8_MMA(ai, bj, At, Bt) do { __builtin_amdgcn_s_setprio(1); _Pragma("unroll") for (int m = 0; m < 4; ++m) _Pragma("unroll") for (int n = 0; n < 2; ++n) _Pragma("unroll") for (int k = 0; k < 2; ++k) \
;         acc[ai][bj][m][n] = __builtin_amdgcn_mfma_f32_16x16x32_bf16(Bt[n][k], At[m][k], acc[ai][bj][m][n], 0, 0, 0); __builtin_amdgcn_s_setprio(0); } while (0)
; #define PG8_WAIT_V(n) asm volatile("s_waitcnt vmcnt(" #n ")" ::: "memory")
; #define PG8_WAIT_L(n) asm volatile("s_waitcnt lgkmcnt(" #n ")" ::: "memory")
; #define PG8_BAR __builtin_amdgcn_s_barrier()
; #define PG8_SCHED __builtin_amdgcn_sched_barrier(0)
; template <class Epi, class Sched, bool ALIGN_EPI = false, bool SP2 = false>
; __device__ __forceinline__ void gemm_phase(PG8_LAS unsigned char* lds, const Gemm g, const Sched& S, const Epi& E) {
;     ...
;             PG8_LDB(B0, 0, 0); PG8_LDB(B1, 0, 1); PG8_SCHED; PG8_LDA(At, 0, 0); PG8_STAGE(PG8_SA(1, 1), a1 + hstep, voffA);
;             PG8_WAIT_V(8); PG8_WAIT_L(0); PG8_BAR; PG8_MMA(0, 0, At, B0); PG8_MMA(0, 1, At, B1); PG8_BAR; PG8_SCHED;
;             PG8_LDA(At, 0, 1); PG8_STAGE(PG8_SB(0, 0), b2, voffB); PG8_STAGE(PG8_SB(0, 1), b2 + hstep, voffB); PG8_STAGE(PG8_SA(0, 0), a2, voffA);
;             PG8_WAIT_V(8); PG8_WAIT_L(0); PG8_BAR; PG8_MMA(1, 0, At, B0); PG8_MMA(1, 1, At, B1); PG8_BAR; PG8_SCHED;
.Lprio_done_86:
.LBB0_86:
	s_add_u32 s26, s38, 0xfff80080
	s_addc_u32 s27, s39, -1
	s_add_i32 s55, 0, 0x10000
	s_cmp_eq_u32 s54, 28
	s_cselect_b32 s27, s29, s27
	s_cselect_b32 s26, s50, s26
	v_add_u32_e32 v142, s55, v147
	s_cselect_b32 s41, s19, s53
	s_cselect_b32 s40, s51, s52
	s_add_i32 s58, 0, 0x14000
	ds_read_b128 v[148:151], v142
	ds_read_b128 v[156:159], v142 offset:1024
	ds_read_b128 v[160:163], v142 offset:2048
	ds_read_b128 v[164:167], v142 offset:3072
	v_add_u32_e32 v142, s58, v147
	ds_read_b128 v[168:171], v142
	ds_read_b128 v[184:187], v142 offset:1024
	ds_read_b128 v[188:191], v142 offset:2048
	ds_read_b128 v[192:195], v142 offset:3072
	v_lshl_add_u64 v[144:145], s[38:39], 0, v[140:141]
	s_add_i32 m0, s25, 0xc000
	ds_read_b128 v[196:199], v155
	ds_read_b128 v[200:203], v155 offset:1024
	ds_read_b128 v[204:207], v155 offset:2048
	ds_read_b128 v[208:211], v155 offset:3072
	ds_read_b128 v[212:215], v155 offset:4096
	ds_read_b128 v[216:219], v155 offset:5120
	ds_read_b128 v[220:223], v155 offset:6144
	ds_read_b128 v[224:227], v155 offset:7168
	global_load_lds_dwordx4 v[144:145], off
	v_lshl_add_u64 v[144:145], s[38:39], 0, v[138:139]
	s_add_i32 m0, s25, 0xe000
	s_nop 0
	global_load_lds_dwordx4 v[144:145], off
	s_waitcnt vmcnt(8)
	s_waitcnt lgkmcnt(0)
	s_barrier
	v_mfma_f32_16x16x32_bf16 v[128:131], v[148:151], v[196:199], v[128:131]
	v_mfma_f32_16x16x32_bf16 v[124:127], v[160:163], v[196:199], v[124:127]
	v_mfma_f32_16x16x32_bf16 v[112:115], v[148:151], v[204:207], v[112:115]
	v_mfma_f32_16x16x32_bf16 v[108:111], v[160:163], v[204:207], v[108:111]
	v_mfma_f32_16x16x32_bf16 v[96:99], v[148:151], v[212:215], v[96:99]
	v_mfma_f32_16x16x32_bf16 v[92:95], v[160:163], v[212:215], v[92:95]
	v_mfma_f32_16x16x32_bf16 v[80:83], v[148:151], v[220:223], v[80:83]
	v_mfma_f32_16x16x32_bf16 v[76:79], v[160:163], v[220:223], v[76:79]
	v_mfma_f32_16x16x32_bf16 v[128:131], v[156:159], v[200:203], v[128:131]
	v_mfma_f32_16x16x32_bf16 v[124:127], v[164:167], v[200:203], v[124:127]
	v_mfma_f32_16x16x32_bf16 v[112:115], v[156:159], v[208:211], v[112:115]
	v_mfma_f32_16x16x32_bf16 v[108:111], v[164:167], v[208:211], v[108:111]
	v_mfma_f32_16x16x32_bf16 v[96:99], v[156:159], v[216:219], v[96:99]
	v_mfma_f32_16x16x32_bf16 v[92:95], v[164:167], v[216:219], v[92:95]
	v_mfma_f32_16x16x32_bf16 v[80:83], v[156:159], v[224:227], v[80:83]
	v_mfma_f32_16x16x32_bf16 v[76:79], v[164:167], v[224:227], v[76:79]
	v_mfma_f32_16x16x32_bf16 v[120:123], v[168:171], v[196:199], v[120:123]
	v_mfma_f32_16x16x32_bf16 v[116:119], v[188:191], v[196:199], v[116:119]
	v_mfma_f32_16x16x32_bf16 v[104:107], v[168:171], v[204:207], v[104:107]
	v_mfma_f32_16x16x32_bf16 v[100:103], v[188:191], v[204:207], v[100:103]
	v_mfma_f32_16x16x32_bf16 v[88:91], v[168:171], v[212:215], v[88:91]
	v_mfma_f32_16x16x32_bf16 v[84:87], v[188:191], v[212:215], v[84:87]
	v_mfma_f32_16x16x32_bf16 v[72:75], v[168:171], v[220:223], v[72:75]
	v_mfma_f32_16x16x32_bf16 v[68:71], v[188:191], v[220:223], v[68:71]
	v_mfma_f32_16x16x32_bf16 v[120:123], v[184:187], v[200:203], v[120:123]
	v_mfma_f32_16x16x32_bf16 v[116:119], v[192:195], v[200:203], v[116:119]
	v_mfma_f32_16x16x32_bf16 v[104:107], v[184:187], v[208:211], v[104:107]
	v_mfma_f32_16x16x32_bf16 v[100:103], v[192:195], v[208:211], v[100:103]
	v_mfma_f32_16x16x32_bf16 v[88:91], v[184:187], v[216:219], v[88:91]
	v_mfma_f32_16x16x32_bf16 v[84:87], v[192:195], v[216:219], v[84:87]
	v_mfma_f32_16x16x32_bf16 v[72:75], v[184:187], v[224:227], v[72:75]
	v_mfma_f32_16x16x32_bf16 v[68:71], v[192:195], v[224:227], v[68:71]
	s_barrier
	s_add_i32 s55, s55, s24
	v_lshl_add_u64 v[144:145], s[40:41], 0, v[174:175]
	s_mov_b32 m0, s55
	ds_read_b128 v[196:199], v155 offset:16384
	ds_read_b128 v[200:203], v155 offset:17408
	ds_read_b128 v[204:207], v155 offset:18432
	ds_read_b128 v[208:211], v155 offset:19456
	ds_read_b128 v[212:215], v155 offset:20480
	ds_read_b128 v[216:219], v155 offset:21504
	ds_read_b128 v[220:223], v155 offset:22528
	ds_read_b128 v[224:227], v155 offset:23552
	global_load_lds_dwordx4 v[144:145], off
	s_add_i32 m0, s55, 0x2000
	s_add_u32 s56, s40, 0x80000
	v_lshl_add_u64 v[228:229], s[40:41], 0, v[132:133]
	s_addc_u32 s57, s41, 0
	s_add_i32 s55, s58, s24
	global_load_lds_dwordx4 v[228:229], off
	v_lshl_add_u64 v[230:231], s[56:57], 0, v[174:175]
	s_mov_b32 m0, s55
	v_lshl_add_u64 v[232:233], s[26:27], 0, v[134:135]
	global_load_lds_dwordx4 v[230:231], off
	v_lshl_add_u64 v[230:231], s[56:57], 0, v[132:133]
	s_add_i32 m0, s55, 0x2000
	s_nop 0
	global_load_lds_dwordx4 v[230:231], off
	v_lshl_add_u64 v[230:231], s[26:27], 0, v[136:137]
	s_mov_b32 m0, s25
	s_nop 0
	global_load_lds_dwordx4 v[230:231], off
	s_mov_b32 m0, s42
	s_nop 0
	global_load_lds_dwordx4 v[232:233], off
	s_waitcnt vmcnt(8)
	s_waitcnt lgkmcnt(0)
	s_barrier
; #define PG8_STAGE(bufoff, gbase, voff) do { _Pragma("unroll") for (int _i = 0; _i < 2; ++_i) \
;         __builtin_amdgcn_global_load_lds((const unsigned*)((const char*)(gbase) + (voff)[_i]), (PG8_LAS unsigned*)(lds + (bufoff) + ldsw + _i * 8192), 16, 0, 0); } while (0)
; #define PG8_LDA(dst, b, h) do { _Pragma("unroll") for (int m = 0; m < 4; ++m) _Pragma("unroll") for (int k = 0; k < 2; ++k) dst[m][k] = *(const PG8_LAS bf16x8*)(lds + PG8_SA(b, h) + aoff + m * 2048 + k * 1024); } while (0)
; #define PG8_LDB(dst, b, h) do { _Pragma("unroll") for (int n = 0; n < 2; ++n) _Pragma("unroll") for (int k = 0; k < 2; ++k) dst[n][k] = *(const PG8_LAS bf16x8*)(lds + PG8_SB(b, h) + boff + n * 2048 + k * 1024); } while (0)
; #define PG8_MMA(ai, bj, At, Bt) do { __builtin_amdgcn_s_setprio(1); _Pragma("unroll") for (int m = 0; m < 4; ++m) _Pragma("unroll") for (int n = 0; n < 2; ++n) _Pragma("unroll") for (int k = 0; k < 2; ++k) \
;         acc[ai][bj][m][n] = __builtin_amdgcn_mfma_f32_16x16x32_bf16(Bt[n][k], At[m][k], acc[ai][bj][m][n], 0, 0, 0); __builtin_amdgcn_s_setprio(0); } while (0)
; #define PG8_WAIT_V(n) asm volatile("s_waitcnt vmcnt(" #n ")" ::: "memory")
; #define PG8_WAIT_L(n) asm volatile("s_waitcnt lgkmcnt(" #n ")" ::: "memory")
; #define PG8_BAR __builtin_amdgcn_s_barrier()
; #define PG8_SCHED __builtin_amdgcn_sched_barrier(0)
; template <class Epi, class Sched, bool ALIGN_EPI = false, bool SP2 = false>
; __device__ __forceinline__ void gemm_phase(PG8_LAS unsigned char* lds, const Gemm g, const Sched& S, const Epi& E) {
;     ...
;             PG8_WAIT_V(8); PG8_WAIT_L(0); PG8_BAR; PG8_MMA(1, 0, At, B0); PG8_MMA(1, 1, At, B1); PG8_BAR; PG8_SCHED;
;             PG8_LDB(B0, 1, 0); PG8_LDB(B1, 1, 1); PG8_SCHED; PG8_LDA(At, 1, 0); PG8_STAGE(PG8_SA(0, 1), a2 + hstep, voffA);
;             PG8_WAIT_V(8); PG8_WAIT_L(0); PG8_BAR; PG8_MMA(0, 0, At, B0); PG8_MMA(0, 1, At, B1); PG8_BAR; PG8_SCHED;
	v_mfma_f32_16x16x32_bf16 v[64:67], v[148:151], v[196:199], v[64:67]
	v_mfma_f32_16x16x32_bf16 v[60:63], v[160:163], v[196:199], v[60:63]
	v_mfma_f32_16x16x32_bf16 v[52:55], v[148:151], v[204:207], v[52:55]
	v_mfma_f32_16x16x32_bf16 v[44:47], v[160:163], v[204:207], v[44:47]
	v_mfma_f32_16x16x32_bf16 v[36:39], v[148:151], v[212:215], v[36:39]
	v_mfma_f32_16x16x32_bf16 v[28:31], v[160:163], v[212:215], v[28:31]
	v_mfma_f32_16x16x32_bf16 v[20:23], v[148:151], v[220:223], v[20:23]
	v_mfma_f32_16x16x32_bf16 v[12:15], v[160:163], v[220:223], v[12:15]
	v_mfma_f32_16x16x32_bf16 v[64:67], v[156:159], v[200:203], v[64:67]
	v_mfma_f32_16x16x32_bf16 v[60:63], v[164:167], v[200:203], v[60:63]
	v_mfma_f32_16x16x32_bf16 v[52:55], v[156:159], v[208:211], v[52:55]
	v_mfma_f32_16x16x32_bf16 v[44:47], v[164:167], v[208:211], v[44:47]
	v_mfma_f32_16x16x32_bf16 v[36:39], v[156:159], v[216:219], v[36:39]
	v_mfma_f32_16x16x32_bf16 v[28:31], v[164:167], v[216:219], v[28:31]
	v_mfma_f32_16x16x32_bf16 v[20:23], v[156:159], v[224:227], v[20:23]
	v_mfma_f32_16x16x32_bf16 v[12:15], v[164:167], v[224:227], v[12:15]
	v_mfma_f32_16x16x32_bf16 v[56:59], v[168:171], v[196:199], v[56:59]
	v_mfma_f32_16x16x32_bf16 v[48:51], v[188:191], v[196:199], v[48:51]
	v_mfma_f32_16x16x32_bf16 v[40:43], v[168:171], v[204:207], v[40:43]
	v_mfma_f32_16x16x32_bf16 v[32:35], v[188:191], v[204:207], v[32:35]
	v_mfma_f32_16x16x32_bf16 v[24:27], v[168:171], v[212:215], v[24:27]
	v_mfma_f32_16x16x32_bf16 v[16:19], v[188:191], v[212:215], v[16:19]
	v_mfma_f32_16x16x32_bf16 v[8:11], v[168:171], v[220:223], v[8:11]
	v_mfma_f32_16x16x32_bf16 v[4:7], v[188:191], v[220:223], v[4:7]
	v_mfma_f32_16x16x32_bf16 v[56:59], v[184:187], v[200:203], v[56:59]
	v_mfma_f32_16x16x32_bf16 v[48:51], v[192:195], v[200:203], v[48:51]
	v_mfma_f32_16x16x32_bf16 v[40:43], v[184:187], v[208:211], v[40:43]
	v_mfma_f32_16x16x32_bf16 v[32:35], v[192:195], v[208:211], v[32:35]
	v_mfma_f32_16x16x32_bf16 v[24:27], v[184:187], v[216:219], v[24:27]
	v_mfma_f32_16x16x32_bf16 v[16:19], v[192:195], v[216:219], v[16:19]
	v_mfma_f32_16x16x32_bf16 v[8:11], v[184:187], v[224:227], v[8:11]
	v_mfma_f32_16x16x32_bf16 v[4:7], v[192:195], v[224:227], v[4:7]
	s_barrier
	s_add_i32 s55, 0, 0x18000
	v_add_u32_e32 v142, s55, v147
	s_add_i32 s56, 0, 0x1c000
	ds_read_b128 v[148:151], v142
	ds_read_b128 v[156:159], v142 offset:1024
	ds_read_b128 v[160:163], v142 offset:2048
	ds_read_b128 v[164:167], v142 offset:3072
	v_add_u32_e32 v142, s56, v147
	ds_read_b128 v[168:171], v142
	ds_read_b128 v[184:187], v142 offset:1024
	ds_read_b128 v[188:191], v142 offset:2048
	ds_read_b128 v[192:195], v142 offset:3072
	s_add_u32 s26, s26, 0x80000
	s_addc_u32 s27, s27, 0
	s_mov_b32 m0, s43
	v_lshl_add_u64 v[234:235], s[26:27], 0, v[136:137]
	ds_read_b128 v[196:199], v155 offset:32768
	ds_read_b128 v[200:203], v155 offset:33792
	ds_read_b128 v[204:207], v155 offset:34816
	ds_read_b128 v[208:211], v155 offset:35840
	ds_read_b128 v[212:215], v155 offset:36864
	ds_read_b128 v[216:219], v155 offset:37888
	ds_read_b128 v[220:223], v155 offset:38912
	ds_read_b128 v[224:227], v155 offset:39936
	global_load_lds_dwordx4 v[234:235], off
	v_lshl_add_u64 v[234:235], s[26:27], 0, v[134:135]
	s_mov_b32 m0, s44
	s_nop 0
	global_load_lds_dwordx4 v[234:235], off
	s_waitcnt vmcnt(8)
	s_waitcnt lgkmcnt(0)
	s_barrier
	v_mfma_f32_16x16x32_bf16 v[128:131], v[148:151], v[196:199], v[128:131]
	v_mfma_f32_16x16x32_bf16 v[124:127], v[160:163], v[196:199], v[124:127]
	v_mfma_f32_16x16x32_bf16 v[112:115], v[148:151], v[204:207], v[112:115]
	v_mfma_f32_16x16x32_bf16 v[108:111], v[160:163], v[204:207], v[108:111]
	v_mfma_f32_16x16x32_bf16 v[96:99], v[148:151], v[212:215], v[96:99]
	v_mfma_f32_16x16x32_bf16 v[92:95], v[160:163], v[212:215], v[92:95]
	v_mfma_f32_16x16x32_bf16 v[80:83], v[148:151], v[220:223], v[80:83]
	v_mfma_f32_16x16x32_bf16 v[76:79], v[160:163], v[220:223], v[76:79]
	v_mfma_f32_16x16x32_bf16 v[128:131], v[156:159], v[200:203], v[128:131]
	v_mfma_f32_16x16x32_bf16 v[124:127], v[164:167], v[200:203], v[124:127]
	v_mfma_f32_16x16x32_bf16 v[112:115], v[156:159], v[208:211], v[112:115]
	v_mfma_f32_16x16x32_bf16 v[108:111], v[164:167], v[208:211], v[108:111]
	v_mfma_f32_16x16x32_bf16 v[96:99], v[156:159], v[216:219], v[96:99]
	v_mfma_f32_16x16x32_bf16 v[92:95], v[164:167], v[216:219], v[92:95]
	v_mfma_f32_16x16x32_bf16 v[80:83], v[156:159], v[224:227], v[80:83]
	v_mfma_f32_16x16x32_bf16 v[76:79], v[164:167], v[224:227], v[76:79]
	v_mfma_f32_16x16x32_bf16 v[120:123], v[168:171], v[196:199], v[120:123]
	v_mfma_f32_16x16x32_bf16 v[116:119], v[188:191], v[196:199], v[116:119]
	v_mfma_f32_16x16x32_bf16 v[104:107], v[168:171], v[204:207], v[104:107]
	v_mfma_f32_16x16x32_bf16 v[100:103], v[188:191], v[204:207], v[100:103]
	v_mfma_f32_16x16x32_bf16 v[88:91], v[168:171], v[212:215], v[88:91]
	v_mfma_f32_16x16x32_bf16 v[84:87], v[188:191], v[212:215], v[84:87]
	v_mfma_f32_16x16x32_bf16 v[72:75], v[168:171], v[220:223], v[72:75]
	v_mfma_f32_16x16x32_bf16 v[68:71], v[188:191], v[220:223], v[68:71]
	v_mfma_f32_16x16x32_bf16 v[120:123], v[184:187], v[200:203], v[120:123]
	v_mfma_f32_16x16x32_bf16 v[116:119], v[192:195], v[200:203], v[116:119]
	v_mfma_f32_16x16x32_bf16 v[104:107], v[184:187], v[208:211], v[104:107]
	v_mfma_f32_16x16x32_bf16 v[100:103], v[192:195], v[208:211], v[100:103]
	v_mfma_f32_16x16x32_bf16 v[88:91], v[184:187], v[216:219], v[88:91]
	v_mfma_f32_16x16x32_bf16 v[84:87], v[192:195], v[216:219], v[84:87]
	v_mfma_f32_16x16x32_bf16 v[72:75], v[184:187], v[224:227], v[72:75]
	v_mfma_f32_16x16x32_bf16 v[68:71], v[192:195], v[224:227], v[68:71]
	s_barrier
; #define PG8_STAGE(bufoff, gbase, voff) do { _Pragma("unroll") for (int _i = 0; _i < 2; ++_i) \
;         __builtin_amdgcn_global_load_lds((const unsigned*)((const char*)(gbase) + (voff)[_i]), (PG8_LAS unsigned*)(lds + (bufoff) + ldsw + _i * 8192), 16, 0, 0); } while (0)
; #define PG8_LDA(dst, b, h) do { _Pragma("unroll") for (int m = 0; m < 4; ++m) _Pragma("unroll") for (int k = 0; k < 2; ++k) dst[m][k] = *(const PG8_LAS bf16x8*)(lds + PG8_SA(b, h) + aoff + m * 2048 + k * 1024); } while (0)
; #define PG8_MMA(ai, bj, At, Bt) do { __builtin_amdgcn_s_setprio(1); _Pragma("unroll") for (int m = 0; m < 4; ++m) _Pragma("unroll") for (int n = 0; n < 2; ++n) _Pragma("unroll") for (int k = 0; k < 2; ++k) \
;         acc[ai][bj][m][n] = __builtin_amdgcn_mfma_f32_16x16x32_bf16(Bt[n][k], At[m][k], acc[ai][bj][m][n], 0, 0, 0); __builtin_amdgcn_s_setprio(0); } while (0)
; #define PG8_WAIT_V(n) asm volatile("s_waitcnt vmcnt(" #n ")" ::: "memory")
; #define PG8_WAIT_L(n) asm volatile("s_waitcnt lgkmcnt(" #n ")" ::: "memory")
; #define PG8_BAR __builtin_amdgcn_s_barrier()
; #define PG8_SCHED __builtin_amdgcn_sched_barrier(0)
; template <class Epi, class Sched, bool ALIGN_EPI = false, bool SP2 = false>
; __device__ __forceinline__ void gemm_phase(PG8_LAS unsigned char* lds, const Gemm g, const Sched& S, const Epi& E) {
;     ...
;             PG8_LDA(At, 1, 1); PG8_STAGE(PG8_SB(1, 0), b3, voffB); PG8_STAGE(PG8_SB(1, 1), b3 + hstep, voffB); PG8_STAGE(PG8_SA(1, 0), a3, voffA);
;             PG8_WAIT_V(8); PG8_WAIT_L(0); PG8_BAR; PG8_MMA(1, 0, At, B0); PG8_MMA(1, 1, At, B1); PG8_BAR; PG8_SCHED;
	s_add_i32 s26, s55, s24
	v_lshl_add_u64 v[144:145], v[144:145], 0, s[10:11]
	s_mov_b32 m0, s26
	ds_read_b128 v[196:199], v155 offset:49152
	ds_read_b128 v[200:203], v155 offset:50176
	ds_read_b128 v[204:207], v155 offset:51200
	ds_read_b128 v[208:211], v155 offset:52224
	ds_read_b128 v[212:215], v155 offset:53248
	ds_read_b128 v[216:219], v155 offset:54272
	ds_read_b128 v[220:223], v155 offset:55296
	ds_read_b128 v[224:227], v155 offset:56320
	global_load_lds_dwordx4 v[144:145], off
	s_add_i32 m0, s26, 0x2000
	s_add_u32 s26, s40, 0x80080
	v_lshl_add_u64 v[144:145], v[228:229], 0, s[10:11]
	s_addc_u32 s27, s41, 0
	s_add_i32 s40, s56, s24
	global_load_lds_dwordx4 v[144:145], off
	v_lshl_add_u64 v[144:145], s[26:27], 0, v[174:175]
	s_mov_b32 m0, s40
	s_nop 0
	global_load_lds_dwordx4 v[144:145], off
	v_lshl_add_u64 v[144:145], s[26:27], 0, v[132:133]
	s_add_i32 m0, s40, 0x2000
	s_nop 0
	global_load_lds_dwordx4 v[144:145], off
	v_lshl_add_u64 v[144:145], v[230:231], 0, s[10:11]
	s_mov_b32 m0, s20
	s_nop 0
	global_load_lds_dwordx4 v[144:145], off
	v_lshl_add_u64 v[144:145], v[232:233], 0, s[10:11]
	s_mov_b32 m0, s45
	s_nop 0
	global_load_lds_dwordx4 v[144:145], off
	s_waitcnt vmcnt(8)
	s_waitcnt lgkmcnt(0)
	s_barrier
	v_mfma_f32_16x16x32_bf16 v[64:67], v[148:151], v[196:199], v[64:67]
	v_mfma_f32_16x16x32_bf16 v[60:63], v[160:163], v[196:199], v[60:63]
	v_mfma_f32_16x16x32_bf16 v[52:55], v[148:151], v[204:207], v[52:55]
	v_mfma_f32_16x16x32_bf16 v[44:47], v[160:163], v[204:207], v[44:47]
	v_mfma_f32_16x16x32_bf16 v[36:39], v[148:151], v[212:215], v[36:39]
	v_mfma_f32_16x16x32_bf16 v[28:31], v[160:163], v[212:215], v[28:31]
	v_mfma_f32_16x16x32_bf16 v[20:23], v[148:151], v[220:223], v[20:23]
	v_mfma_f32_16x16x32_bf16 v[12:15], v[160:163], v[220:223], v[12:15]
	v_mfma_f32_16x16x32_bf16 v[64:67], v[156:159], v[200:203], v[64:67]
	v_mfma_f32_16x16x32_bf16 v[60:63], v[164:167], v[200:203], v[60:63]
	v_mfma_f32_16x16x32_bf16 v[52:55], v[156:159], v[208:211], v[52:55]
	v_mfma_f32_16x16x32_bf16 v[44:47], v[164:167], v[208:211], v[44:47]
	v_mfma_f32_16x16x32_bf16 v[36:39], v[156:159], v[216:219], v[36:39]
	v_mfma_f32_16x16x32_bf16 v[28:31], v[164:167], v[216:219], v[28:31]
	v_mfma_f32_16x16x32_bf16 v[20:23], v[156:159], v[224:227], v[20:23]
	v_mfma_f32_16x16x32_bf16 v[12:15], v[164:167], v[224:227], v[12:15]
	v_mfma_f32_16x16x32_bf16 v[56:59], v[168:171], v[196:199], v[56:59]
	v_mfma_f32_16x16x32_bf16 v[48:51], v[188:191], v[196:199], v[48:51]
	v_mfma_f32_16x16x32_bf16 v[40:43], v[168:171], v[204:207], v[40:43]
	v_mfma_f32_16x16x32_bf16 v[32:35], v[188:191], v[204:207], v[32:35]
	v_mfma_f32_16x16x32_bf16 v[24:27], v[168:171], v[212:215], v[24:27]
	v_mfma_f32_16x16x32_bf16 v[16:19], v[188:191], v[212:215], v[16:19]
	v_mfma_f32_16x16x32_bf16 v[8:11], v[168:171], v[220:223], v[8:11]
	v_mfma_f32_16x16x32_bf16 v[4:7], v[188:191], v[220:223], v[4:7]
	v_mfma_f32_16x16x32_bf16 v[56:59], v[184:187], v[200:203], v[56:59]
	v_mfma_f32_16x16x32_bf16 v[48:51], v[192:195], v[200:203], v[48:51]
	v_mfma_f32_16x16x32_bf16 v[40:43], v[184:187], v[208:211], v[40:43]
	v_mfma_f32_16x16x32_bf16 v[32:35], v[192:195], v[208:211], v[32:35]
	v_mfma_f32_16x16x32_bf16 v[24:27], v[184:187], v[216:219], v[24:27]
	v_mfma_f32_16x16x32_bf16 v[16:19], v[192:195], v[216:219], v[16:19]
	v_mfma_f32_16x16x32_bf16 v[8:11], v[184:187], v[224:227], v[8:11]
	v_mfma_f32_16x16x32_bf16 v[4:7], v[192:195], v[224:227], v[4:7]
	s_barrier
	s_add_i32 s54, s54, 2
	s_add_u32 s52, s52, 0x100
	s_addc_u32 s53, s53, 0
	s_add_u32 s38, s38, 0x100
	s_addc_u32 s39, s39, 0
	s_cmp_gt_u32 s54, 29
	s_cbranch_scc0 .LBB0_86
	s_and_b64 vcc, exec, s[16:17]
	s_cbranch_vccz .LBB0_89
	s_barrier

; #define PG8_STAGE(bufoff, gbase, voff) do { _Pragma("unroll") for (int _i = 0; _i < 2; ++_i) \
;         __builtin_amdgcn_global_load_lds((const unsigned*)((const char*)(gbase) + (voff)[_i]), (PG8_LAS unsigned*)(lds + (bufoff) + ldsw + _i * 8192), 16, 0, 0); } while (0)
; #define PG8_LDA(dst, b, h) do { _Pragma("unroll") for (int m = 0; m < 4; ++m) _Pragma("unroll") for (int k = 0; k < 2; ++k) dst[m][k] = *(const PG8_LAS bf16x8*)(lds + PG8_SA(b, h) + aoff + m * 2048 + k * 1024); } while (0)
; #define PG8_LDB(dst, b, h) do { _Pragma("unroll") for (int n = 0; n < 2; ++n) _Pragma("unroll") for (int k = 0; k < 2; ++k) dst[n][k] = *(const PG8_LAS bf16x8*)(lds + PG8_SB(b, h) + boff + n * 2048 + k * 1024); } while (0)
; #define PG8_MMA(ai, bj, At, Bt) do { __builtin_amdgcn_s_setprio(1); _Pragma("unroll") for (int m = 0; m < 4; ++m) _Pragma("unroll") for (int n = 0; n < 2; ++n) _Pragma("unroll") for (int k = 0; k < 2; ++k) \
;         acc[ai][bj][m][n] = __builtin_amdgcn_mfma_f32_16x16x32_bf16(Bt[n][k], At[m][k], acc[ai][bj][m][n], 0, 0, 0); __builtin_amdgcn_s_setprio(0); } while (0)
; #define PG8_WAIT_V(n) asm volatile("s_waitcnt vmcnt(" #n ")" ::: "memory")
; #define PG8_WAIT_L(n) asm volatile("s_waitcnt lgkmcnt(" #n ")" ::: "memory")
; #define PG8_BAR __builtin_amdgcn_s_barrier()
; #define PG8_SCHED __builtin_amdgcn_sched_barrier(0)
; template <class Epi, class Sched, bool ALIGN_EPI = false, bool SP2 = false>
; __device__ __forceinline__ void gemm_phase(PG8_LAS unsigned char* lds, const Gemm g, const Sched& S, const Epi& E) {
;     ...
;             PG8_LDB(B0, 0, 0); PG8_LDB(B1, 0, 1); PG8_SCHED; PG8_LDA(At, 0, 0); PG8_STAGE(PG8_SA(1, 1), a1 + hstep, voffA);
;             PG8_WAIT_V(8); PG8_WAIT_L(0); PG8_BAR; PG8_MMA(0, 0, At, B0); PG8_MMA(0, 1, At, B1); PG8_BAR; PG8_SCHED;
;             PG8_LDA(At, 0, 1); PG8_STAGE(PG8_SB(0, 0), b2, voffB); PG8_STAGE(PG8_SB(0, 1), b2 + hstep, voffB); PG8_STAGE(PG8_SA(0, 0), a2, voffA);
;             PG8_WAIT_V(8); PG8_WAIT_L(0); PG8_BAR; PG8_MMA(1, 0, At, B0); PG8_MMA(1, 1, At, B1); PG8_BAR; PG8_SCHED;
.Lprio_done_407:
.LBB0_407:
	s_add_u32 s14, s0, 0xfff80080
	s_addc_u32 s15, s1, -1
	s_add_i32 s59, 0, 0x10000
	s_cmp_eq_u32 s58, 28
	s_cselect_b32 s17, s23, s15
	s_cselect_b32 s16, s24, s14
	s_cselect_b32 s15, s25, s57
	s_cselect_b32 s14, s49, s51
	s_add_i32 s62, 0, 0x14000
	v_add_u32_e32 v154, s59, v171
	v_add_u32_e32 v185, s62, v171
	ds_read_b128 v[100:103], v154
	ds_read_b128 v[104:107], v154 offset:1024
	ds_read_b128 v[140:143], v154 offset:2048
	ds_read_b128 v[154:157], v154 offset:3072
	ds_read_b128 v[158:161], v185
	ds_read_b128 v[162:165], v185 offset:1024
	ds_read_b128 v[166:169], v185 offset:2048
	ds_read_b128 v[186:189], v185 offset:3072
	v_lshl_add_u64 v[222:223], s[0:1], 0, v[152:153]
	s_add_i32 m0, s29, 0xc000
	ds_read_b128 v[190:193], v184
	ds_read_b128 v[194:197], v184 offset:1024
	ds_read_b128 v[198:201], v184 offset:2048
	ds_read_b128 v[202:205], v184 offset:3072
	ds_read_b128 v[206:209], v184 offset:4096
	ds_read_b128 v[210:213], v184 offset:5120
	ds_read_b128 v[214:217], v184 offset:6144
	ds_read_b128 v[218:221], v184 offset:7168
	global_load_lds_dwordx4 v[222:223], off
	v_lshl_add_u64 v[222:223], s[0:1], 0, v[150:151]
	s_add_i32 m0, s29, 0xe000
	s_nop 0
	global_load_lds_dwordx4 v[222:223], off
	s_waitcnt vmcnt(8)
	s_waitcnt lgkmcnt(0)
	s_barrier
	v_mfma_f32_16x16x32_bf16 v[136:139], v[100:103], v[190:193], v[136:139]
	v_mfma_f32_16x16x32_bf16 v[132:135], v[140:143], v[190:193], v[132:135]
	v_mfma_f32_16x16x32_bf16 v[128:131], v[100:103], v[198:201], v[128:131]
	v_mfma_f32_16x16x32_bf16 v[124:127], v[140:143], v[198:201], v[124:127]
	v_mfma_f32_16x16x32_bf16 v[120:123], v[100:103], v[206:209], v[120:123]
	v_mfma_f32_16x16x32_bf16 v[116:119], v[140:143], v[206:209], v[116:119]
	v_mfma_f32_16x16x32_bf16 v[112:115], v[100:103], v[214:217], v[112:115]
	v_mfma_f32_16x16x32_bf16 v[108:111], v[140:143], v[214:217], v[108:111]
	v_mfma_f32_16x16x32_bf16 v[136:139], v[104:107], v[194:197], v[136:139]
	v_mfma_f32_16x16x32_bf16 v[132:135], v[154:157], v[194:197], v[132:135]
	v_mfma_f32_16x16x32_bf16 v[128:131], v[104:107], v[202:205], v[128:131]
	v_mfma_f32_16x16x32_bf16 v[124:127], v[154:157], v[202:205], v[124:127]
	v_mfma_f32_16x16x32_bf16 v[120:123], v[104:107], v[210:213], v[120:123]
	v_mfma_f32_16x16x32_bf16 v[116:119], v[154:157], v[210:213], v[116:119]
	v_mfma_f32_16x16x32_bf16 v[112:115], v[104:107], v[218:221], v[112:115]
	v_mfma_f32_16x16x32_bf16 v[108:111], v[154:157], v[218:221], v[108:111]
	v_mfma_f32_16x16x32_bf16 v[64:67], v[158:161], v[190:193], v[64:67]
	v_mfma_f32_16x16x32_bf16 v[60:63], v[166:169], v[190:193], v[60:63]
	v_mfma_f32_16x16x32_bf16 v[56:59], v[158:161], v[198:201], v[56:59]
	v_mfma_f32_16x16x32_bf16 v[52:55], v[166:169], v[198:201], v[52:55]
	v_mfma_f32_16x16x32_bf16 v[48:51], v[158:161], v[206:209], v[48:51]
	v_mfma_f32_16x16x32_bf16 v[44:47], v[166:169], v[206:209], v[44:47]
	v_mfma_f32_16x16x32_bf16 v[40:43], v[158:161], v[214:217], v[40:43]
	v_mfma_f32_16x16x32_bf16 v[36:39], v[166:169], v[214:217], v[36:39]
	v_mfma_f32_16x16x32_bf16 v[64:67], v[162:165], v[194:197], v[64:67]
	v_mfma_f32_16x16x32_bf16 v[60:63], v[186:189], v[194:197], v[60:63]
	v_mfma_f32_16x16x32_bf16 v[56:59], v[162:165], v[202:205], v[56:59]
	v_mfma_f32_16x16x32_bf16 v[52:55], v[186:189], v[202:205], v[52:55]
	v_mfma_f32_16x16x32_bf16 v[48:51], v[162:165], v[210:213], v[48:51]
	v_mfma_f32_16x16x32_bf16 v[44:47], v[186:189], v[210:213], v[44:47]
	v_mfma_f32_16x16x32_bf16 v[40:43], v[162:165], v[218:221], v[40:43]
	v_mfma_f32_16x16x32_bf16 v[36:39], v[186:189], v[218:221], v[36:39]
	s_barrier
	s_add_i32 s59, s59, s28
	v_lshl_add_u64 v[222:223], s[14:15], 0, v[174:175]
	s_mov_b32 m0, s59
	ds_read_b128 v[190:193], v184 offset:16384
	ds_read_b128 v[194:197], v184 offset:17408
	ds_read_b128 v[198:201], v184 offset:18432
	ds_read_b128 v[202:205], v184 offset:19456
	ds_read_b128 v[206:209], v184 offset:20480
	ds_read_b128 v[210:213], v184 offset:21504
	ds_read_b128 v[214:217], v184 offset:22528
	ds_read_b128 v[218:221], v184 offset:23552
	global_load_lds_dwordx4 v[222:223], off
	s_add_i32 m0, s59, 0x2000
	s_add_u32 s60, s14, 0x80000
	v_lshl_add_u64 v[224:225], s[14:15], 0, v[144:145]
	s_addc_u32 s61, s15, 0
	s_add_i32 s59, s62, s28
	global_load_lds_dwordx4 v[224:225], off
	v_lshl_add_u64 v[226:227], s[60:61], 0, v[174:175]
	s_mov_b32 m0, s59
	v_lshl_add_u64 v[228:229], s[16:17], 0, v[146:147]
	global_load_lds_dwordx4 v[226:227], off
	v_lshl_add_u64 v[226:227], s[60:61], 0, v[144:145]
	s_add_i32 m0, s59, 0x2000
	s_nop 0
	global_load_lds_dwordx4 v[226:227], off
	v_lshl_add_u64 v[226:227], s[16:17], 0, v[148:149]
	s_mov_b32 m0, s29
	s_nop 0
	global_load_lds_dwordx4 v[226:227], off
	s_mov_b32 m0, s30
	s_nop 0
	global_load_lds_dwordx4 v[228:229], off
	s_waitcnt vmcnt(8)
	s_waitcnt lgkmcnt(0)
	s_barrier
; #define PG8_STAGE(bufoff, gbase, voff) do { _Pragma("unroll") for (int _i = 0; _i < 2; ++_i) \
;         __builtin_amdgcn_global_load_lds((const unsigned*)((const char*)(gbase) + (voff)[_i]), (PG8_LAS unsigned*)(lds + (bufoff) + ldsw + _i * 8192), 16, 0, 0); } while (0)
; #define PG8_LDA(dst, b, h) do { _Pragma("unroll") for (int m = 0; m < 4; ++m) _Pragma("unroll") for (int k = 0; k < 2; ++k) dst[m][k] = *(const PG8_LAS bf16x8*)(lds + PG8_SA(b, h) + aoff + m * 2048 + k * 1024); } while (0)
; #define PG8_LDB(dst, b, h) do { _Pragma("unroll") for (int n = 0; n < 2; ++n) _Pragma("unroll") for (int k = 0; k < 2; ++k) dst[n][k] = *(const PG8_LAS bf16x8*)(lds + PG8_SB(b, h) + boff + n * 2048 + k * 1024); } while (0)
; #define PG8_MMA(ai, bj, At, Bt) do { __builtin_amdgcn_s_setprio(1); _Pragma("unroll") for (int m = 0; m < 4; ++m) _Pragma("unroll") for (int n = 0; n < 2; ++n) _Pragma("unroll") for (int k = 0; k < 2; ++k) \
;         acc[ai][bj][m][n] = __builtin_amdgcn_mfma_f32_16x16x32_bf16(Bt[n][k], At[m][k], acc[ai][bj][m][n], 0, 0, 0); __builtin_amdgcn_s_setprio(0); } while (0)
; #define PG8_WAIT_V(n) asm volatile("s_waitcnt vmcnt(" #n ")" ::: "memory")
; #define PG8_WAIT_L(n) asm volatile("s_waitcnt lgkmcnt(" #n ")" ::: "memory")
; #define PG8_BAR __builtin_amdgcn_s_barrier()
; #define PG8_SCHED __builtin_amdgcn_sched_barrier(0)
; template <class Epi, class Sched, bool ALIGN_EPI = false, bool SP2 = false>
; __device__ __forceinline__ void gemm_phase(PG8_LAS unsigned char* lds, const Gemm g, const Sched& S, const Epi& E) {
;     ...
;             PG8_WAIT_V(8); PG8_WAIT_L(0); PG8_BAR; PG8_MMA(1, 0, At, B0); PG8_MMA(1, 1, At, B1); PG8_BAR; PG8_SCHED;
;             PG8_LDB(B0, 1, 0); PG8_LDB(B1, 1, 1); PG8_SCHED; PG8_LDA(At, 1, 0); PG8_STAGE(PG8_SA(0, 1), a2 + hstep, voffA);
;             PG8_WAIT_V(8); PG8_WAIT_L(0); PG8_BAR; PG8_MMA(0, 0, At, B0); PG8_MMA(0, 1, At, B1); PG8_BAR; PG8_SCHED;
	v_mfma_f32_16x16x32_bf16 v[96:99], v[100:103], v[190:193], v[96:99]
	v_mfma_f32_16x16x32_bf16 v[92:95], v[140:143], v[190:193], v[92:95]
	v_mfma_f32_16x16x32_bf16 v[88:91], v[100:103], v[198:201], v[88:91]
	v_mfma_f32_16x16x32_bf16 v[84:87], v[140:143], v[198:201], v[84:87]
	v_mfma_f32_16x16x32_bf16 v[80:83], v[100:103], v[206:209], v[80:83]
	v_mfma_f32_16x16x32_bf16 v[76:79], v[140:143], v[206:209], v[76:79]
	v_mfma_f32_16x16x32_bf16 v[72:75], v[100:103], v[214:217], v[72:75]
	v_mfma_f32_16x16x32_bf16 v[68:71], v[140:143], v[214:217], v[68:71]
	v_mfma_f32_16x16x32_bf16 v[96:99], v[104:107], v[194:197], v[96:99]
	v_mfma_f32_16x16x32_bf16 v[92:95], v[154:157], v[194:197], v[92:95]
	v_mfma_f32_16x16x32_bf16 v[88:91], v[104:107], v[202:205], v[88:91]
	v_mfma_f32_16x16x32_bf16 v[84:87], v[154:157], v[202:205], v[84:87]
	v_mfma_f32_16x16x32_bf16 v[80:83], v[104:107], v[210:213], v[80:83]
	v_mfma_f32_16x16x32_bf16 v[76:79], v[154:157], v[210:213], v[76:79]
	v_mfma_f32_16x16x32_bf16 v[72:75], v[104:107], v[218:221], v[72:75]
	v_mfma_f32_16x16x32_bf16 v[68:71], v[154:157], v[218:221], v[68:71]
	v_mfma_f32_16x16x32_bf16 v[32:35], v[158:161], v[190:193], v[32:35]
	v_mfma_f32_16x16x32_bf16 v[28:31], v[166:169], v[190:193], v[28:31]
	v_mfma_f32_16x16x32_bf16 v[24:27], v[158:161], v[198:201], v[24:27]
	v_mfma_f32_16x16x32_bf16 v[20:23], v[166:169], v[198:201], v[20:23]
	v_mfma_f32_16x16x32_bf16 v[16:19], v[158:161], v[206:209], v[16:19]
	v_mfma_f32_16x16x32_bf16 v[12:15], v[166:169], v[206:209], v[12:15]
	v_mfma_f32_16x16x32_bf16 v[8:11], v[158:161], v[214:217], v[8:11]
	v_mfma_f32_16x16x32_bf16 v[4:7], v[166:169], v[214:217], v[4:7]
	v_mfma_f32_16x16x32_bf16 v[32:35], v[162:165], v[194:197], v[32:35]
	v_mfma_f32_16x16x32_bf16 v[28:31], v[186:189], v[194:197], v[28:31]
	v_mfma_f32_16x16x32_bf16 v[24:27], v[162:165], v[202:205], v[24:27]
	v_mfma_f32_16x16x32_bf16 v[20:23], v[186:189], v[202:205], v[20:23]
	v_mfma_f32_16x16x32_bf16 v[16:19], v[162:165], v[210:213], v[16:19]
	v_mfma_f32_16x16x32_bf16 v[12:15], v[186:189], v[210:213], v[12:15]
	v_mfma_f32_16x16x32_bf16 v[8:11], v[162:165], v[218:221], v[8:11]
	v_mfma_f32_16x16x32_bf16 v[4:7], v[186:189], v[218:221], v[4:7]
	s_barrier
	s_add_i32 s59, 0, 0x18000
	s_add_i32 s60, 0, 0x1c000
	v_add_u32_e32 v154, s59, v171
	v_add_u32_e32 v185, s60, v171
	ds_read_b128 v[100:103], v154
	ds_read_b128 v[104:107], v154 offset:1024
	ds_read_b128 v[140:143], v154 offset:2048
	ds_read_b128 v[154:157], v154 offset:3072
	ds_read_b128 v[158:161], v185
	ds_read_b128 v[162:165], v185 offset:1024
	ds_read_b128 v[166:169], v185 offset:2048
	ds_read_b128 v[186:189], v185 offset:3072
	s_add_u32 s16, s16, 0x80000
	s_addc_u32 s17, s17, 0
	s_mov_b32 m0, s31
	v_lshl_add_u64 v[230:231], s[16:17], 0, v[148:149]
	ds_read_b128 v[190:193], v184 offset:32768
	ds_read_b128 v[194:197], v184 offset:33792
	ds_read_b128 v[198:201], v184 offset:34816
	ds_read_b128 v[202:205], v184 offset:35840
	ds_read_b128 v[206:209], v184 offset:36864
	ds_read_b128 v[210:213], v184 offset:37888
	ds_read_b128 v[214:217], v184 offset:38912
	ds_read_b128 v[218:221], v184 offset:39936
	global_load_lds_dwordx4 v[230:231], off
	v_lshl_add_u64 v[230:231], s[16:17], 0, v[146:147]
	s_mov_b32 m0, s34
	s_nop 0
	global_load_lds_dwordx4 v[230:231], off
	s_waitcnt vmcnt(8)
	s_waitcnt lgkmcnt(0)
	s_barrier
	v_mfma_f32_16x16x32_bf16 v[136:139], v[100:103], v[190:193], v[136:139]
	v_mfma_f32_16x16x32_bf16 v[132:135], v[140:143], v[190:193], v[132:135]
	v_mfma_f32_16x16x32_bf16 v[128:131], v[100:103], v[198:201], v[128:131]
	v_mfma_f32_16x16x32_bf16 v[124:127], v[140:143], v[198:201], v[124:127]
	v_mfma_f32_16x16x32_bf16 v[120:123], v[100:103], v[206:209], v[120:123]
	v_mfma_f32_16x16x32_bf16 v[116:119], v[140:143], v[206:209], v[116:119]
	v_mfma_f32_16x16x32_bf16 v[112:115], v[100:103], v[214:217], v[112:115]
	v_mfma_f32_16x16x32_bf16 v[108:111], v[140:143], v[214:217], v[108:111]
	v_mfma_f32_16x16x32_bf16 v[136:139], v[104:107], v[194:197], v[136:139]
	v_mfma_f32_16x16x32_bf16 v[132:135], v[154:157], v[194:197], v[132:135]
	v_mfma_f32_16x16x32_bf16 v[128:131], v[104:107], v[202:205], v[128:131]
	v_mfma_f32_16x16x32_bf16 v[124:127], v[154:157], v[202:205], v[124:127]
	v_mfma_f32_16x16x32_bf16 v[120:123], v[104:107], v[210:213], v[120:123]
	v_mfma_f32_16x16x32_bf16 v[116:119], v[154:157], v[210:213], v[116:119]
	v_mfma_f32_16x16x32_bf16 v[112:115], v[104:107], v[218:221], v[112:115]
	v_mfma_f32_16x16x32_bf16 v[108:111], v[154:157], v[218:221], v[108:111]
	v_mfma_f32_16x16x32_bf16 v[64:67], v[158:161], v[190:193], v[64:67]
	v_mfma_f32_16x16x32_bf16 v[60:63], v[166:169], v[190:193], v[60:63]
	v_mfma_f32_16x16x32_bf16 v[56:59], v[158:161], v[198:201], v[56:59]
	v_mfma_f32_16x16x32_bf16 v[52:55], v[166:169], v[198:201], v[52:55]
	v_mfma_f32_16x16x32_bf16 v[48:51], v[158:161], v[206:209], v[48:51]
	v_mfma_f32_16x16x32_bf16 v[44:47], v[166:169], v[206:209], v[44:47]
	v_mfma_f32_16x16x32_bf16 v[40:43], v[158:161], v[214:217], v[40:43]
	v_mfma_f32_16x16x32_bf16 v[36:39], v[166:169], v[214:217], v[36:39]
	v_mfma_f32_16x16x32_bf16 v[64:67], v[162:165], v[194:197], v[64:67]
	v_mfma_f32_16x16x32_bf16 v[60:63], v[186:189], v[194:197], v[60:63]
	v_mfma_f32_16x16x32_bf16 v[56:59], v[162:165], v[202:205], v[56:59]
	v_mfma_f32_16x16x32_bf16 v[52:55], v[186:189], v[202:205], v[52:55]
	v_mfma_f32_16x16x32_bf16 v[48:51], v[162:165], v[210:213], v[48:51]
	v_mfma_f32_16x16x32_bf16 v[44:47], v[186:189], v[210:213], v[44:47]
	v_mfma_f32_16x16x32_bf16 v[40:43], v[162:165], v[218:221], v[40:43]
	v_mfma_f32_16x16x32_bf16 v[36:39], v[186:189], v[218:221], v[36:39]
	s_barrier
; #define PG8_STAGE(bufoff, gbase, voff) do { _Pragma("unroll") for (int _i = 0; _i < 2; ++_i) \
;         __builtin_amdgcn_global_load_lds((const unsigned*)((const char*)(gbase) + (voff)[_i]), (PG8_LAS unsigned*)(lds + (bufoff) + ldsw + _i * 8192), 16, 0, 0); } while (0)
; #define PG8_LDA(dst, b, h) do { _Pragma("unroll") for (int m = 0; m < 4; ++m) _Pragma("unroll") for (int k = 0; k < 2; ++k) dst[m][k] = *(const PG8_LAS bf16x8*)(lds + PG8_SA(b, h) + aoff + m * 2048 + k * 1024); } while (0)
; #define PG8_MMA(ai, bj, At, Bt) do { __builtin_amdgcn_s_setprio(1); _Pragma("unroll") for (int m = 0; m < 4; ++m) _Pragma("unroll") for (int n = 0; n < 2; ++n) _Pragma("unroll") for (int k = 0; k < 2; ++k) \
;         acc[ai][bj][m][n] = __builtin_amdgcn_mfma_f32_16x16x32_bf16(Bt[n][k], At[m][k], acc[ai][bj][m][n], 0, 0, 0); __builtin_amdgcn_s_setprio(0); } while (0)
; #define PG8_WAIT_V(n) asm volatile("s_waitcnt vmcnt(" #n ")" ::: "memory")
; #define PG8_WAIT_L(n) asm volatile("s_waitcnt lgkmcnt(" #n ")" ::: "memory")
; #define PG8_BAR __builtin_amdgcn_s_barrier()
; #define PG8_SCHED __builtin_amdgcn_sched_barrier(0)
; template <class Epi, class Sched, bool ALIGN_EPI = false, bool SP2 = false>
; __device__ __forceinline__ void gemm_phase(PG8_LAS unsigned char* lds, const Gemm g, const Sched& S, const Epi& E) {
;     ...
;             PG8_LDA(At, 1, 1); PG8_STAGE(PG8_SB(1, 0), b3, voffB); PG8_STAGE(PG8_SB(1, 1), b3 + hstep, voffB); PG8_STAGE(PG8_SA(1, 0), a3, voffA);
;             PG8_WAIT_V(8); PG8_WAIT_L(0); PG8_BAR; PG8_MMA(1, 0, At, B0); PG8_MMA(1, 1, At, B1); PG8_BAR; PG8_SCHED;
	s_add_i32 s16, s59, s28
	v_lshl_add_u64 v[222:223], v[222:223], 0, s[10:11]
	s_mov_b32 m0, s16
	ds_read_b128 v[190:193], v184 offset:49152
	ds_read_b128 v[194:197], v184 offset:50176
	ds_read_b128 v[198:201], v184 offset:51200
	ds_read_b128 v[202:205], v184 offset:52224
	ds_read_b128 v[206:209], v184 offset:53248
	ds_read_b128 v[210:213], v184 offset:54272
	ds_read_b128 v[214:217], v184 offset:55296
	ds_read_b128 v[218:221], v184 offset:56320
	global_load_lds_dwordx4 v[222:223], off
	s_add_i32 m0, s16, 0x2000
	s_add_u32 s14, s14, 0x80080
	v_lshl_add_u64 v[222:223], v[224:225], 0, s[10:11]
	s_addc_u32 s15, s15, 0
	s_add_i32 s16, s60, s28
	global_load_lds_dwordx4 v[222:223], off
	v_lshl_add_u64 v[222:223], s[14:15], 0, v[174:175]
	s_mov_b32 m0, s16
	s_nop 0
	global_load_lds_dwordx4 v[222:223], off
	v_lshl_add_u64 v[222:223], s[14:15], 0, v[144:145]
	s_add_i32 m0, s16, 0x2000
	s_nop 0
	global_load_lds_dwordx4 v[222:223], off
	v_lshl_add_u64 v[222:223], v[226:227], 0, s[10:11]
	s_mov_b32 m0, s35
	s_nop 0
	global_load_lds_dwordx4 v[222:223], off
	v_lshl_add_u64 v[222:223], v[228:229], 0, s[10:11]
	s_mov_b32 m0, s38
	s_nop 0
	global_load_lds_dwordx4 v[222:223], off
	s_waitcnt vmcnt(8)
	s_waitcnt lgkmcnt(0)
	s_barrier
	v_mfma_f32_16x16x32_bf16 v[96:99], v[100:103], v[190:193], v[96:99]
	v_mfma_f32_16x16x32_bf16 v[92:95], v[140:143], v[190:193], v[92:95]
	v_mfma_f32_16x16x32_bf16 v[88:91], v[100:103], v[198:201], v[88:91]
	v_mfma_f32_16x16x32_bf16 v[84:87], v[140:143], v[198:201], v[84:87]
	v_mfma_f32_16x16x32_bf16 v[80:83], v[100:103], v[206:209], v[80:83]
	v_mfma_f32_16x16x32_bf16 v[76:79], v[140:143], v[206:209], v[76:79]
	v_mfma_f32_16x16x32_bf16 v[72:75], v[100:103], v[214:217], v[72:75]
	v_mfma_f32_16x16x32_bf16 v[68:71], v[140:143], v[214:217], v[68:71]
	v_mfma_f32_16x16x32_bf16 v[96:99], v[104:107], v[194:197], v[96:99]
	v_mfma_f32_16x16x32_bf16 v[92:95], v[154:157], v[194:197], v[92:95]
	v_mfma_f32_16x16x32_bf16 v[88:91], v[104:107], v[202:205], v[88:91]
	v_mfma_f32_16x16x32_bf16 v[84:87], v[154:157], v[202:205], v[84:87]
	v_mfma_f32_16x16x32_bf16 v[80:83], v[104:107], v[210:213], v[80:83]
	v_mfma_f32_16x16x32_bf16 v[76:79], v[154:157], v[210:213], v[76:79]
	v_mfma_f32_16x16x32_bf16 v[72:75], v[104:107], v[218:221], v[72:75]
	v_mfma_f32_16x16x32_bf16 v[68:71], v[154:157], v[218:221], v[68:71]
	v_mfma_f32_16x16x32_bf16 v[32:35], v[158:161], v[190:193], v[32:35]
	v_mfma_f32_16x16x32_bf16 v[28:31], v[166:169], v[190:193], v[28:31]
	v_mfma_f32_16x16x32_bf16 v[24:27], v[158:161], v[198:201], v[24:27]
	v_mfma_f32_16x16x32_bf16 v[20:23], v[166:169], v[198:201], v[20:23]
	v_mfma_f32_16x16x32_bf16 v[16:19], v[158:161], v[206:209], v[16:19]
	v_mfma_f32_16x16x32_bf16 v[12:15], v[166:169], v[206:209], v[12:15]
	v_mfma_f32_16x16x32_bf16 v[8:11], v[158:161], v[214:217], v[8:11]
	v_mfma_f32_16x16x32_bf16 v[4:7], v[166:169], v[214:217], v[4:7]
	v_mfma_f32_16x16x32_bf16 v[32:35], v[162:165], v[194:197], v[32:35]
	v_mfma_f32_16x16x32_bf16 v[28:31], v[186:189], v[194:197], v[28:31]
	v_mfma_f32_16x16x32_bf16 v[24:27], v[162:165], v[202:205], v[24:27]
	v_mfma_f32_16x16x32_bf16 v[20:23], v[186:189], v[202:205], v[20:23]
	v_mfma_f32_16x16x32_bf16 v[16:19], v[162:165], v[210:213], v[16:19]
	v_mfma_f32_16x16x32_bf16 v[12:15], v[186:189], v[210:213], v[12:15]
	v_mfma_f32_16x16x32_bf16 v[8:11], v[162:165], v[218:221], v[8:11]
	v_mfma_f32_16x16x32_bf16 v[4:7], v[186:189], v[218:221], v[4:7]
	s_barrier
	s_add_i32 s58, s58, 2
	s_add_u32 s51, s51, 0x100
	s_addc_u32 s57, s57, 0
	s_add_u32 s0, s0, 0x100
	s_addc_u32 s1, s1, 0
	s_cmp_gt_u32 s58, 29
	s_cbranch_scc0 .LBB0_407
	s_and_b64 vcc, exec, s[46:47]
	s_cbranch_vccz .LBB0_410
	s_barrier

; #define PG8_STAGE(bufoff, gbase, voff) do { _Pragma("unroll") for (int _i = 0; _i < 2; ++_i) \
;         __builtin_amdgcn_global_load_lds((const unsigned*)((const char*)(gbase) + (voff)[_i]), (PG8_LAS unsigned*)(lds + (bufoff) + ldsw + _i * 8192), 16, 0, 0); } while (0)
; #define PG8_LDA(dst, b, h) do { _Pragma("unroll") for (int m = 0; m < 4; ++m) _Pragma("unroll") for (int k = 0; k < 2; ++k) dst[m][k] = *(const PG8_LAS bf16x8*)(lds + PG8_SA(b, h) + aoff + m * 2048 + k * 1024); } while (0)
; #define PG8_LDB(dst, b, h) do { _Pragma("unroll") for (int n = 0; n < 2; ++n) _Pragma("unroll") for (int k = 0; k < 2; ++k) dst[n][k] = *(const PG8_LAS bf16x8*)(lds + PG8_SB(b, h) + boff + n * 2048 + k * 1024); } while (0)
; #define PG8_MMA(ai, bj, At, Bt) do { __builtin_amdgcn_s_setprio(1); _Pragma("unroll") for (int m = 0; m < 4; ++m) _Pragma("unroll") for (int n = 0; n < 2; ++n) _Pragma("unroll") for (int k = 0; k < 2; ++k) \
;         acc[ai][bj][m][n] = __builtin_amdgcn_mfma_f32_16x16x32_bf16(Bt[n][k], At[m][k], acc[ai][bj][m][n], 0, 0, 0); __builtin_amdgcn_s_setprio(0); } while (0)
; #define PG8_WAIT_V(n) asm volatile("s_waitcnt vmcnt(" #n ")" ::: "memory")
; #define PG8_WAIT_L(n) asm volatile("s_waitcnt lgkmcnt(" #n ")" ::: "memory")
; #define PG8_BAR __builtin_amdgcn_s_barrier()
; #define PG8_SCHED __builtin_amdgcn_sched_barrier(0)
; template <class Epi, class Sched, bool ALIGN_EPI = false, bool SP2 = false>
; __device__ __forceinline__ void gemm_phase(PG8_LAS unsigned char* lds, const Gemm g, const Sched& S, const Epi& E) {
;     ...
;             PG8_LDB(B0, 0, 0); PG8_LDB(B1, 0, 1); PG8_SCHED; PG8_LDA(At, 0, 0); PG8_STAGE(PG8_SA(1, 1), a1 + hstep, voffA);
;             PG8_WAIT_V(8); PG8_WAIT_L(0); PG8_BAR; PG8_MMA(0, 0, At, B0); PG8_MMA(0, 1, At, B1); PG8_BAR; PG8_SCHED;
;             PG8_LDA(At, 0, 1); PG8_STAGE(PG8_SB(0, 0), b2, voffB); PG8_STAGE(PG8_SB(0, 1), b2 + hstep, voffB); PG8_STAGE(PG8_SA(0, 0), a2, voffA);
;             PG8_WAIT_V(8); PG8_WAIT_L(0); PG8_BAR; PG8_MMA(1, 0, At, B0); PG8_MMA(1, 1, At, B1); PG8_BAR; PG8_SCHED;
.Lprio_done_485:
.LBB0_485:
	s_add_u32 s14, s0, 0xfff00080
	s_addc_u32 s15, s1, -1
	s_add_i32 s61, 0, 0x10000
	s_cmp_eq_u32 s60, 60
	s_cselect_b32 s17, s23, s15
	s_cselect_b32 s16, s24, s14
	s_cselect_b32 s15, s25, s59
	s_cselect_b32 s14, s51, s53
	s_add_i32 s64, 0, 0x14000
	v_add_u32_e32 v144, s61, v188
	v_add_u32_e32 v170, s64, v188
	ds_read_b128 v[100:103], v144
	ds_read_b128 v[104:107], v144 offset:1024
	ds_read_b128 v[140:143], v144 offset:2048
	ds_read_b128 v[144:147], v144 offset:3072
	ds_read_b128 v[158:161], v170
	ds_read_b128 v[162:165], v170 offset:1024
	ds_read_b128 v[166:169], v170 offset:2048
	ds_read_b128 v[184:187], v170 offset:3072
	v_lshl_add_u64 v[170:171], s[0:1], 0, v[156:157]
	s_add_i32 m0, s29, 0xc000
	ds_read_b128 v[192:195], v190
	ds_read_b128 v[196:199], v190 offset:1024
	ds_read_b128 v[200:203], v190 offset:2048
	ds_read_b128 v[204:207], v190 offset:3072
	ds_read_b128 v[208:211], v190 offset:4096
	ds_read_b128 v[212:215], v190 offset:5120
	ds_read_b128 v[216:219], v190 offset:6144
	ds_read_b128 v[220:223], v190 offset:7168
	global_load_lds_dwordx4 v[170:171], off
	v_lshl_add_u64 v[170:171], s[0:1], 0, v[154:155]
	s_add_i32 m0, s29, 0xe000
	s_nop 0
	global_load_lds_dwordx4 v[170:171], off
	s_waitcnt vmcnt(8)
	s_waitcnt lgkmcnt(0)
	s_barrier
	v_mfma_f32_16x16x32_bf16 v[136:139], v[100:103], v[192:195], v[136:139]
	v_mfma_f32_16x16x32_bf16 v[132:135], v[140:143], v[192:195], v[132:135]
	v_mfma_f32_16x16x32_bf16 v[128:131], v[100:103], v[200:203], v[128:131]
	v_mfma_f32_16x16x32_bf16 v[124:127], v[140:143], v[200:203], v[124:127]
	v_mfma_f32_16x16x32_bf16 v[120:123], v[100:103], v[208:211], v[120:123]
	v_mfma_f32_16x16x32_bf16 v[116:119], v[140:143], v[208:211], v[116:119]
	v_mfma_f32_16x16x32_bf16 v[112:115], v[100:103], v[216:219], v[112:115]
	v_mfma_f32_16x16x32_bf16 v[108:111], v[140:143], v[216:219], v[108:111]
	v_mfma_f32_16x16x32_bf16 v[136:139], v[104:107], v[196:199], v[136:139]
	v_mfma_f32_16x16x32_bf16 v[132:135], v[144:147], v[196:199], v[132:135]
	v_mfma_f32_16x16x32_bf16 v[128:131], v[104:107], v[204:207], v[128:131]
	v_mfma_f32_16x16x32_bf16 v[124:127], v[144:147], v[204:207], v[124:127]
	v_mfma_f32_16x16x32_bf16 v[120:123], v[104:107], v[212:215], v[120:123]
	v_mfma_f32_16x16x32_bf16 v[116:119], v[144:147], v[212:215], v[116:119]
	v_mfma_f32_16x16x32_bf16 v[112:115], v[104:107], v[220:223], v[112:115]
	v_mfma_f32_16x16x32_bf16 v[108:111], v[144:147], v[220:223], v[108:111]
	v_mfma_f32_16x16x32_bf16 v[64:67], v[158:161], v[192:195], v[64:67]
	v_mfma_f32_16x16x32_bf16 v[60:63], v[166:169], v[192:195], v[60:63]
	v_mfma_f32_16x16x32_bf16 v[56:59], v[158:161], v[200:203], v[56:59]
	v_mfma_f32_16x16x32_bf16 v[52:55], v[166:169], v[200:203], v[52:55]
	v_mfma_f32_16x16x32_bf16 v[48:51], v[158:161], v[208:211], v[48:51]
	v_mfma_f32_16x16x32_bf16 v[44:47], v[166:169], v[208:211], v[44:47]
	v_mfma_f32_16x16x32_bf16 v[40:43], v[158:161], v[216:219], v[40:43]
	v_mfma_f32_16x16x32_bf16 v[36:39], v[166:169], v[216:219], v[36:39]
	v_mfma_f32_16x16x32_bf16 v[64:67], v[162:165], v[196:199], v[64:67]
	v_mfma_f32_16x16x32_bf16 v[60:63], v[184:187], v[196:199], v[60:63]
	v_mfma_f32_16x16x32_bf16 v[56:59], v[162:165], v[204:207], v[56:59]
	v_mfma_f32_16x16x32_bf16 v[52:55], v[184:187], v[204:207], v[52:55]
	v_mfma_f32_16x16x32_bf16 v[48:51], v[162:165], v[212:215], v[48:51]
	v_mfma_f32_16x16x32_bf16 v[44:47], v[184:187], v[212:215], v[44:47]
	v_mfma_f32_16x16x32_bf16 v[40:43], v[162:165], v[220:223], v[40:43]
	v_mfma_f32_16x16x32_bf16 v[36:39], v[184:187], v[220:223], v[36:39]
	s_barrier
	s_add_i32 s61, s61, s28
	v_lshl_add_u64 v[170:171], s[14:15], 0, v[174:175]
	s_mov_b32 m0, s61
	ds_read_b128 v[192:195], v190 offset:16384
	ds_read_b128 v[196:199], v190 offset:17408
	ds_read_b128 v[200:203], v190 offset:18432
	ds_read_b128 v[204:207], v190 offset:19456
	ds_read_b128 v[208:211], v190 offset:20480
	ds_read_b128 v[212:215], v190 offset:21504
	ds_read_b128 v[216:219], v190 offset:22528
	ds_read_b128 v[220:223], v190 offset:23552
	global_load_lds_dwordx4 v[170:171], off
	s_add_i32 m0, s61, 0x2000
	s_add_u32 s62, s14, 0x100000
	v_lshl_add_u64 v[224:225], s[14:15], 0, v[148:149]
	s_addc_u32 s63, s15, 0
	s_add_i32 s61, s64, s28
	global_load_lds_dwordx4 v[224:225], off
	v_lshl_add_u64 v[226:227], s[62:63], 0, v[174:175]
	s_mov_b32 m0, s61
	v_lshl_add_u64 v[228:229], s[16:17], 0, v[150:151]
	global_load_lds_dwordx4 v[226:227], off
	v_lshl_add_u64 v[226:227], s[62:63], 0, v[148:149]
	s_add_i32 m0, s61, 0x2000
	s_nop 0
	global_load_lds_dwordx4 v[226:227], off
	v_lshl_add_u64 v[226:227], s[16:17], 0, v[152:153]
	s_mov_b32 m0, s29
	s_nop 0
	global_load_lds_dwordx4 v[226:227], off
	s_mov_b32 m0, s30
	s_nop 0
	global_load_lds_dwordx4 v[228:229], off
	s_waitcnt vmcnt(8)
	s_waitcnt lgkmcnt(0)
	s_barrier
; #define PG8_STAGE(bufoff, gbase, voff) do { _Pragma("unroll") for (int _i = 0; _i < 2; ++_i) \
;         __builtin_amdgcn_global_load_lds((const unsigned*)((const char*)(gbase) + (voff)[_i]), (PG8_LAS unsigned*)(lds + (bufoff) + ldsw + _i * 8192), 16, 0, 0); } while (0)
; #define PG8_LDA(dst, b, h) do { _Pragma("unroll") for (int m = 0; m < 4; ++m) _Pragma("unroll") for (int k = 0; k < 2; ++k) dst[m][k] = *(const PG8_LAS bf16x8*)(lds + PG8_SA(b, h) + aoff + m * 2048 + k * 1024); } while (0)
; #define PG8_LDB(dst, b, h) do { _Pragma("unroll") for (int n = 0; n < 2; ++n) _Pragma("unroll") for (int k = 0; k < 2; ++k) dst[n][k] = *(const PG8_LAS bf16x8*)(lds + PG8_SB(b, h) + boff + n * 2048 + k * 1024); } while (0)
; #define PG8_MMA(ai, bj, At, Bt) do { __builtin_amdgcn_s_setprio(1); _Pragma("unroll") for (int m = 0; m < 4; ++m) _Pragma("unroll") for (int n = 0; n < 2; ++n) _Pragma("unroll") for (int k = 0; k < 2; ++k) \
;         acc[ai][bj][m][n] = __builtin_amdgcn_mfma_f32_16x16x32_bf16(Bt[n][k], At[m][k], acc[ai][bj][m][n], 0, 0, 0); __builtin_amdgcn_s_setprio(0); } while (0)
; #define PG8_WAIT_V(n) asm volatile("s_waitcnt vmcnt(" #n ")" ::: "memory")
; #define PG8_WAIT_L(n) asm volatile("s_waitcnt lgkmcnt(" #n ")" ::: "memory")
; #define PG8_BAR __builtin_amdgcn_s_barrier()
; #define PG8_SCHED __builtin_amdgcn_sched_barrier(0)
; template <class Epi, class Sched, bool ALIGN_EPI = false, bool SP2 = false>
; __device__ __forceinline__ void gemm_phase(PG8_LAS unsigned char* lds, const Gemm g, const Sched& S, const Epi& E) {
;     ...
;             PG8_WAIT_V(8); PG8_WAIT_L(0); PG8_BAR; PG8_MMA(1, 0, At, B0); PG8_MMA(1, 1, At, B1); PG8_BAR; PG8_SCHED;
;             PG8_LDB(B0, 1, 0); PG8_LDB(B1, 1, 1); PG8_SCHED; PG8_LDA(At, 1, 0); PG8_STAGE(PG8_SA(0, 1), a2 + hstep, voffA);
;             PG8_WAIT_V(8); PG8_WAIT_L(0); PG8_BAR; PG8_MMA(0, 0, At, B0); PG8_MMA(0, 1, At, B1); PG8_BAR; PG8_SCHED;
	v_mfma_f32_16x16x32_bf16 v[96:99], v[100:103], v[192:195], v[96:99]
	v_mfma_f32_16x16x32_bf16 v[92:95], v[140:143], v[192:195], v[92:95]
	v_mfma_f32_16x16x32_bf16 v[88:91], v[100:103], v[200:203], v[88:91]
	v_mfma_f32_16x16x32_bf16 v[84:87], v[140:143], v[200:203], v[84:87]
	v_mfma_f32_16x16x32_bf16 v[80:83], v[100:103], v[208:211], v[80:83]
	v_mfma_f32_16x16x32_bf16 v[76:79], v[140:143], v[208:211], v[76:79]
	v_mfma_f32_16x16x32_bf16 v[72:75], v[100:103], v[216:219], v[72:75]
	v_mfma_f32_16x16x32_bf16 v[68:71], v[140:143], v[216:219], v[68:71]
	v_mfma_f32_16x16x32_bf16 v[96:99], v[104:107], v[196:199], v[96:99]
	v_mfma_f32_16x16x32_bf16 v[92:95], v[144:147], v[196:199], v[92:95]
	v_mfma_f32_16x16x32_bf16 v[88:91], v[104:107], v[204:207], v[88:91]
	v_mfma_f32_16x16x32_bf16 v[84:87], v[144:147], v[204:207], v[84:87]
	v_mfma_f32_16x16x32_bf16 v[80:83], v[104:107], v[212:215], v[80:83]
	v_mfma_f32_16x16x32_bf16 v[76:79], v[144:147], v[212:215], v[76:79]
	v_mfma_f32_16x16x32_bf16 v[72:75], v[104:107], v[220:223], v[72:75]
	v_mfma_f32_16x16x32_bf16 v[68:71], v[144:147], v[220:223], v[68:71]
	v_mfma_f32_16x16x32_bf16 v[32:35], v[158:161], v[192:195], v[32:35]
	v_mfma_f32_16x16x32_bf16 v[28:31], v[166:169], v[192:195], v[28:31]
	v_mfma_f32_16x16x32_bf16 v[24:27], v[158:161], v[200:203], v[24:27]
	v_mfma_f32_16x16x32_bf16 v[20:23], v[166:169], v[200:203], v[20:23]
	v_mfma_f32_16x16x32_bf16 v[16:19], v[158:161], v[208:211], v[16:19]
	v_mfma_f32_16x16x32_bf16 v[12:15], v[166:169], v[208:211], v[12:15]
	v_mfma_f32_16x16x32_bf16 v[8:11], v[158:161], v[216:219], v[8:11]
	v_mfma_f32_16x16x32_bf16 v[4:7], v[166:169], v[216:219], v[4:7]
	v_mfma_f32_16x16x32_bf16 v[32:35], v[162:165], v[196:199], v[32:35]
	v_mfma_f32_16x16x32_bf16 v[28:31], v[184:187], v[196:199], v[28:31]
	v_mfma_f32_16x16x32_bf16 v[24:27], v[162:165], v[204:207], v[24:27]
	v_mfma_f32_16x16x32_bf16 v[20:23], v[184:187], v[204:207], v[20:23]
	v_mfma_f32_16x16x32_bf16 v[16:19], v[162:165], v[212:215], v[16:19]
	v_mfma_f32_16x16x32_bf16 v[12:15], v[184:187], v[212:215], v[12:15]
	v_mfma_f32_16x16x32_bf16 v[8:11], v[162:165], v[220:223], v[8:11]
	v_mfma_f32_16x16x32_bf16 v[4:7], v[184:187], v[220:223], v[4:7]
	s_barrier
	s_add_i32 s61, 0, 0x18000
	s_add_i32 s62, 0, 0x1c000
	v_add_u32_e32 v144, s61, v188
	v_add_u32_e32 v184, s62, v188
	ds_read_b128 v[100:103], v144
	ds_read_b128 v[104:107], v144 offset:1024
	ds_read_b128 v[140:143], v144 offset:2048
	ds_read_b128 v[144:147], v144 offset:3072
	ds_read_b128 v[158:161], v184
	ds_read_b128 v[162:165], v184 offset:1024
	ds_read_b128 v[166:169], v184 offset:2048
	ds_read_b128 v[184:187], v184 offset:3072
	s_add_u32 s16, s16, 0x100000
	s_addc_u32 s17, s17, 0
	s_mov_b32 m0, s31
	v_lshl_add_u64 v[230:231], s[16:17], 0, v[152:153]
	ds_read_b128 v[192:195], v190 offset:32768
	ds_read_b128 v[196:199], v190 offset:33792
	ds_read_b128 v[200:203], v190 offset:34816
	ds_read_b128 v[204:207], v190 offset:35840
	ds_read_b128 v[208:211], v190 offset:36864
	ds_read_b128 v[212:215], v190 offset:37888
	ds_read_b128 v[216:219], v190 offset:38912
	ds_read_b128 v[220:223], v190 offset:39936
	global_load_lds_dwordx4 v[230:231], off
	v_lshl_add_u64 v[230:231], s[16:17], 0, v[150:151]
	s_mov_b32 m0, s34
	s_nop 0
	global_load_lds_dwordx4 v[230:231], off
	s_waitcnt vmcnt(8)
	s_waitcnt lgkmcnt(0)
	s_barrier
	v_mfma_f32_16x16x32_bf16 v[136:139], v[100:103], v[192:195], v[136:139]
	v_mfma_f32_16x16x32_bf16 v[132:135], v[140:143], v[192:195], v[132:135]
	v_mfma_f32_16x16x32_bf16 v[128:131], v[100:103], v[200:203], v[128:131]
	v_mfma_f32_16x16x32_bf16 v[124:127], v[140:143], v[200:203], v[124:127]
	v_mfma_f32_16x16x32_bf16 v[120:123], v[100:103], v[208:211], v[120:123]
	v_mfma_f32_16x16x32_bf16 v[116:119], v[140:143], v[208:211], v[116:119]
	v_mfma_f32_16x16x32_bf16 v[112:115], v[100:103], v[216:219], v[112:115]
	v_mfma_f32_16x16x32_bf16 v[108:111], v[140:143], v[216:219], v[108:111]
	v_mfma_f32_16x16x32_bf16 v[136:139], v[104:107], v[196:199], v[136:139]
	v_mfma_f32_16x16x32_bf16 v[132:135], v[144:147], v[196:199], v[132:135]
	v_mfma_f32_16x16x32_bf16 v[128:131], v[104:107], v[204:207], v[128:131]
	v_mfma_f32_16x16x32_bf16 v[124:127], v[144:147], v[204:207], v[124:127]
	v_mfma_f32_16x16x32_bf16 v[120:123], v[104:107], v[212:215], v[120:123]
	v_mfma_f32_16x16x32_bf16 v[116:119], v[144:147], v[212:215], v[116:119]
	v_mfma_f32_16x16x32_bf16 v[112:115], v[104:107], v[220:223], v[112:115]
	v_mfma_f32_16x16x32_bf16 v[108:111], v[144:147], v[220:223], v[108:111]
	v_mfma_f32_16x16x32_bf16 v[64:67], v[158:161], v[192:195], v[64:67]
	v_mfma_f32_16x16x32_bf16 v[60:63], v[166:169], v[192:195], v[60:63]
	v_mfma_f32_16x16x32_bf16 v[56:59], v[158:161], v[200:203], v[56:59]
	v_mfma_f32_16x16x32_bf16 v[52:55], v[166:169], v[200:203], v[52:55]
	v_mfma_f32_16x16x32_bf16 v[48:51], v[158:161], v[208:211], v[48:51]
	v_mfma_f32_16x16x32_bf16 v[44:47], v[166:169], v[208:211], v[44:47]
	v_mfma_f32_16x16x32_bf16 v[40:43], v[158:161], v[216:219], v[40:43]
	v_mfma_f32_16x16x32_bf16 v[36:39], v[166:169], v[216:219], v[36:39]
	v_mfma_f32_16x16x32_bf16 v[64:67], v[162:165], v[196:199], v[64:67]
	v_mfma_f32_16x16x32_bf16 v[60:63], v[184:187], v[196:199], v[60:63]
	v_mfma_f32_16x16x32_bf16 v[56:59], v[162:165], v[204:207], v[56:59]
	v_mfma_f32_16x16x32_bf16 v[52:55], v[184:187], v[204:207], v[52:55]
	v_mfma_f32_16x16x32_bf16 v[48:51], v[162:165], v[212:215], v[48:51]
	v_mfma_f32_16x16x32_bf16 v[44:47], v[184:187], v[212:215], v[44:47]
	v_mfma_f32_16x16x32_bf16 v[40:43], v[162:165], v[220:223], v[40:43]
	v_mfma_f32_16x16x32_bf16 v[36:39], v[184:187], v[220:223], v[36:39]
	s_barrier
; #define PG8_STAGE(bufoff, gbase, voff) do { _Pragma("unroll") for (int _i = 0; _i < 2; ++_i) \
;         __builtin_amdgcn_global_load_lds((const unsigned*)((const char*)(gbase) + (voff)[_i]), (PG8_LAS unsigned*)(lds + (bufoff) + ldsw + _i * 8192), 16, 0, 0); } while (0)
; #define PG8_LDA(dst, b, h) do { _Pragma("unroll") for (int m = 0; m < 4; ++m) _Pragma("unroll") for (int k = 0; k < 2; ++k) dst[m][k] = *(const PG8_LAS bf16x8*)(lds + PG8_SA(b, h) + aoff + m * 2048 + k * 1024); } while (0)
; #define PG8_MMA(ai, bj, At, Bt) do { __builtin_amdgcn_s_setprio(1); _Pragma("unroll") for (int m = 0; m < 4; ++m) _Pragma("unroll") for (int n = 0; n < 2; ++n) _Pragma("unroll") for (int k = 0; k < 2; ++k) \
;         acc[ai][bj][m][n] = __builtin_amdgcn_mfma_f32_16x16x32_bf16(Bt[n][k], At[m][k], acc[ai][bj][m][n], 0, 0, 0); __builtin_amdgcn_s_setprio(0); } while (0)
; #define PG8_WAIT_V(n) asm volatile("s_waitcnt vmcnt(" #n ")" ::: "memory")
; #define PG8_WAIT_L(n) asm volatile("s_waitcnt lgkmcnt(" #n ")" ::: "memory")
; #define PG8_BAR __builtin_amdgcn_s_barrier()
; #define PG8_SCHED __builtin_amdgcn_sched_barrier(0)
; template <class Epi, class Sched, bool ALIGN_EPI = false, bool SP2 = false>
; __device__ __forceinline__ void gemm_phase(PG8_LAS unsigned char* lds, const Gemm g, const Sched& S, const Epi& E) {
;     ...
;             PG8_LDA(At, 1, 1); PG8_STAGE(PG8_SB(1, 0), b3, voffB); PG8_STAGE(PG8_SB(1, 1), b3 + hstep, voffB); PG8_STAGE(PG8_SA(1, 0), a3, voffA);
;             PG8_WAIT_V(8); PG8_WAIT_L(0); PG8_BAR; PG8_MMA(1, 0, At, B0); PG8_MMA(1, 1, At, B1); PG8_BAR; PG8_SCHED;
	s_add_i32 s16, s61, s28
	v_lshl_add_u64 v[170:171], v[170:171], 0, s[10:11]
	s_mov_b32 m0, s16
	ds_read_b128 v[192:195], v190 offset:49152
	ds_read_b128 v[196:199], v190 offset:50176
	ds_read_b128 v[200:203], v190 offset:51200
	ds_read_b128 v[204:207], v190 offset:52224
	ds_read_b128 v[208:211], v190 offset:53248
	ds_read_b128 v[212:215], v190 offset:54272
	ds_read_b128 v[216:219], v190 offset:55296
	ds_read_b128 v[220:223], v190 offset:56320
	global_load_lds_dwordx4 v[170:171], off
	s_add_i32 m0, s16, 0x2000
	s_add_u32 s14, s14, 0x100080
	v_lshl_add_u64 v[170:171], v[224:225], 0, s[10:11]
	s_addc_u32 s15, s15, 0
	s_add_i32 s16, s62, s28
	global_load_lds_dwordx4 v[170:171], off
	v_lshl_add_u64 v[170:171], s[14:15], 0, v[174:175]
	s_mov_b32 m0, s16
	s_nop 0
	global_load_lds_dwordx4 v[170:171], off
	v_lshl_add_u64 v[170:171], s[14:15], 0, v[148:149]
	s_add_i32 m0, s16, 0x2000
	s_nop 0
	global_load_lds_dwordx4 v[170:171], off
	v_lshl_add_u64 v[170:171], v[226:227], 0, s[10:11]
	s_mov_b32 m0, s35
	s_nop 0
	global_load_lds_dwordx4 v[170:171], off
	v_lshl_add_u64 v[170:171], v[228:229], 0, s[10:11]
	s_mov_b32 m0, s38
	s_nop 0
	global_load_lds_dwordx4 v[170:171], off
	s_waitcnt vmcnt(8)
	s_waitcnt lgkmcnt(0)
	s_barrier
	v_mfma_f32_16x16x32_bf16 v[96:99], v[100:103], v[192:195], v[96:99]
	v_mfma_f32_16x16x32_bf16 v[92:95], v[140:143], v[192:195], v[92:95]
	v_mfma_f32_16x16x32_bf16 v[88:91], v[100:103], v[200:203], v[88:91]
	v_mfma_f32_16x16x32_bf16 v[84:87], v[140:143], v[200:203], v[84:87]
	v_mfma_f32_16x16x32_bf16 v[80:83], v[100:103], v[208:211], v[80:83]
	v_mfma_f32_16x16x32_bf16 v[76:79], v[140:143], v[208:211], v[76:79]
	v_mfma_f32_16x16x32_bf16 v[72:75], v[100:103], v[216:219], v[72:75]
	v_mfma_f32_16x16x32_bf16 v[68:71], v[140:143], v[216:219], v[68:71]
	v_mfma_f32_16x16x32_bf16 v[96:99], v[104:107], v[196:199], v[96:99]
	v_mfma_f32_16x16x32_bf16 v[92:95], v[144:147], v[196:199], v[92:95]
	v_mfma_f32_16x16x32_bf16 v[88:91], v[104:107], v[204:207], v[88:91]
	v_mfma_f32_16x16x32_bf16 v[84:87], v[144:147], v[204:207], v[84:87]
	v_mfma_f32_16x16x32_bf16 v[80:83], v[104:107], v[212:215], v[80:83]
	v_mfma_f32_16x16x32_bf16 v[76:79], v[144:147], v[212:215], v[76:79]
	v_mfma_f32_16x16x32_bf16 v[72:75], v[104:107], v[220:223], v[72:75]
	v_mfma_f32_16x16x32_bf16 v[68:71], v[144:147], v[220:223], v[68:71]
	v_mfma_f32_16x16x32_bf16 v[32:35], v[158:161], v[192:195], v[32:35]
	v_mfma_f32_16x16x32_bf16 v[28:31], v[166:169], v[192:195], v[28:31]
	v_mfma_f32_16x16x32_bf16 v[24:27], v[158:161], v[200:203], v[24:27]
	v_mfma_f32_16x16x32_bf16 v[20:23], v[166:169], v[200:203], v[20:23]
	v_mfma_f32_16x16x32_bf16 v[16:19], v[158:161], v[208:211], v[16:19]
	v_mfma_f32_16x16x32_bf16 v[12:15], v[166:169], v[208:211], v[12:15]
	v_mfma_f32_16x16x32_bf16 v[8:11], v[158:161], v[216:219], v[8:11]
	v_mfma_f32_16x16x32_bf16 v[4:7], v[166:169], v[216:219], v[4:7]
	v_mfma_f32_16x16x32_bf16 v[32:35], v[162:165], v[196:199], v[32:35]
	v_mfma_f32_16x16x32_bf16 v[28:31], v[184:187], v[196:199], v[28:31]
	v_mfma_f32_16x16x32_bf16 v[24:27], v[162:165], v[204:207], v[24:27]
	v_mfma_f32_16x16x32_bf16 v[20:23], v[184:187], v[204:207], v[20:23]
	v_mfma_f32_16x16x32_bf16 v[16:19], v[162:165], v[212:215], v[16:19]
	v_mfma_f32_16x16x32_bf16 v[12:15], v[184:187], v[212:215], v[12:15]
	v_mfma_f32_16x16x32_bf16 v[8:11], v[162:165], v[220:223], v[8:11]
	v_mfma_f32_16x16x32_bf16 v[4:7], v[184:187], v[220:223], v[4:7]
	s_barrier
	s_add_i32 s60, s60, 2
	s_add_u32 s53, s53, 0x100
	s_addc_u32 s59, s59, 0
	s_add_u32 s0, s0, 0x100
	s_addc_u32 s1, s1, 0
	s_cmp_gt_u32 s60, 61
	s_cbranch_scc0 .LBB0_485
	s_and_b64 vcc, exec, s[48:49]
	s_cbranch_vccz .LBB0_488
	s_barrier

; #define PG8_STAGE(bufoff, gbase, voff) do { _Pragma("unroll") for (int _i = 0; _i < 2; ++_i) \
;         __builtin_amdgcn_global_load_lds((const unsigned*)((const char*)(gbase) + (voff)[_i]), (PG8_LAS unsigned*)(lds + (bufoff) + ldsw + _i * 8192), 16, 0, 0); } while (0)
; #define PG8_LDA(dst, b, h) do { _Pragma("unroll") for (int m = 0; m < 4; ++m) _Pragma("unroll") for (int k = 0; k < 2; ++k) dst[m][k] = *(const PG8_LAS bf16x8*)(lds + PG8_SA(b, h) + aoff + m * 2048 + k * 1024); } while (0)
; #define PG8_LDB(dst, b, h) do { _Pragma("unroll") for (int n = 0; n < 2; ++n) _Pragma("unroll") for (int k = 0; k < 2; ++k) dst[n][k] = *(const PG8_LAS bf16x8*)(lds + PG8_SB(b, h) + boff + n * 2048 + k * 1024); } while (0)
; #define PG8_MMA(ai, bj, At, Bt) do { __builtin_amdgcn_s_setprio(1); _Pragma("unroll") for (int m = 0; m < 4; ++m) _Pragma("unroll") for (int n = 0; n < 2; ++n) _Pragma("unroll") for (int k = 0; k < 2; ++k) \
;         acc[ai][bj][m][n] = __builtin_amdgcn_mfma_f32_16x16x32_bf16(Bt[n][k], At[m][k], acc[ai][bj][m][n], 0, 0, 0); __builtin_amdgcn_s_setprio(0); } while (0)
; #define PG8_WAIT_V(n) asm volatile("s_waitcnt vmcnt(" #n ")" ::: "memory")
; #define PG8_WAIT_L(n) asm volatile("s_waitcnt lgkmcnt(" #n ")" ::: "memory")
; #define PG8_BAR __builtin_amdgcn_s_barrier()
; #define PG8_SCHED __builtin_amdgcn_sched_barrier(0)
; template <class Epi, class Sched, bool ALIGN_EPI = false, bool SP2 = false>
; __device__ __forceinline__ void gemm_phase(PG8_LAS unsigned char* lds, const Gemm g, const Sched& S, const Epi& E) {
;     ...
;             PG8_LDB(B0, 0, 0); PG8_LDB(B1, 0, 1); PG8_SCHED; PG8_LDA(At, 0, 0); PG8_STAGE(PG8_SA(1, 1), a1 + hstep, voffA);
;             PG8_WAIT_V(8); PG8_WAIT_L(0); PG8_BAR; PG8_MMA(0, 0, At, B0); PG8_MMA(0, 1, At, B1); PG8_BAR; PG8_SCHED;
;             PG8_LDA(At, 0, 1); PG8_STAGE(PG8_SB(0, 0), b2, voffB); PG8_STAGE(PG8_SB(0, 1), b2 + hstep, voffB); PG8_STAGE(PG8_SA(0, 0), a2, voffA);
;             PG8_WAIT_V(8); PG8_WAIT_L(0); PG8_BAR; PG8_MMA(1, 0, At, B0); PG8_MMA(1, 1, At, B1); PG8_BAR; PG8_SCHED;
.Lprio_done_563:
.LBB0_563:
	s_add_u32 s18, s0, 0xfff80080
	s_addc_u32 s19, s1, -1
	s_add_i32 s64, 0, 0x10000
	s_cmp_eq_u32 s63, 28
	s_cselect_b32 s27, s39, s19
	s_cselect_b32 s26, s59, s18
	s_cselect_b32 s19, s37, s62
	s_cselect_b32 s18, s60, s61
	s_add_i32 s66, 0, 0x14000
	v_add_u32_e32 v144, s64, v167
	v_add_u32_e32 v170, s66, v167
	ds_read_b128 v[132:135], v144
	ds_read_b128 v[136:139], v144 offset:1024
	ds_read_b128 v[140:143], v144 offset:2048
	ds_read_b128 v[144:147], v144 offset:3072
	ds_read_b128 v[158:161], v170
	ds_read_b128 v[162:165], v170 offset:1024
	ds_read_b128 v[184:187], v170 offset:2048
	ds_read_b128 v[188:191], v170 offset:3072
	v_lshl_add_u64 v[170:171], s[0:1], 0, v[156:157]
	s_add_i32 m0, s49, 0xc000
	ds_read_b128 v[192:195], v169
	ds_read_b128 v[196:199], v169 offset:1024
	ds_read_b128 v[200:203], v169 offset:2048
	ds_read_b128 v[204:207], v169 offset:3072
	ds_read_b128 v[208:211], v169 offset:4096
	ds_read_b128 v[212:215], v169 offset:5120
	ds_read_b128 v[216:219], v169 offset:6144
	ds_read_b128 v[220:223], v169 offset:7168
	global_load_lds_dwordx4 v[170:171], off
	v_lshl_add_u64 v[170:171], s[0:1], 0, v[154:155]
	s_add_i32 m0, s49, 0xe000
	s_nop 0
	global_load_lds_dwordx4 v[170:171], off
	s_waitcnt vmcnt(8)
	s_waitcnt lgkmcnt(0)
	s_barrier
	v_mfma_f32_16x16x32_bf16 v[128:131], v[132:135], v[192:195], v[128:131]
	v_mfma_f32_16x16x32_bf16 v[124:127], v[140:143], v[192:195], v[124:127]
	v_mfma_f32_16x16x32_bf16 v[112:115], v[132:135], v[200:203], v[112:115]
	v_mfma_f32_16x16x32_bf16 v[108:111], v[140:143], v[200:203], v[108:111]
	v_mfma_f32_16x16x32_bf16 v[96:99], v[132:135], v[208:211], v[96:99]
	v_mfma_f32_16x16x32_bf16 v[92:95], v[140:143], v[208:211], v[92:95]
	v_mfma_f32_16x16x32_bf16 v[80:83], v[132:135], v[216:219], v[80:83]
	v_mfma_f32_16x16x32_bf16 v[76:79], v[140:143], v[216:219], v[76:79]
	v_mfma_f32_16x16x32_bf16 v[128:131], v[136:139], v[196:199], v[128:131]
	v_mfma_f32_16x16x32_bf16 v[124:127], v[144:147], v[196:199], v[124:127]
	v_mfma_f32_16x16x32_bf16 v[112:115], v[136:139], v[204:207], v[112:115]
	v_mfma_f32_16x16x32_bf16 v[108:111], v[144:147], v[204:207], v[108:111]
	v_mfma_f32_16x16x32_bf16 v[96:99], v[136:139], v[212:215], v[96:99]
	v_mfma_f32_16x16x32_bf16 v[92:95], v[144:147], v[212:215], v[92:95]
	v_mfma_f32_16x16x32_bf16 v[80:83], v[136:139], v[220:223], v[80:83]
	v_mfma_f32_16x16x32_bf16 v[76:79], v[144:147], v[220:223], v[76:79]
	v_mfma_f32_16x16x32_bf16 v[120:123], v[158:161], v[192:195], v[120:123]
	v_mfma_f32_16x16x32_bf16 v[116:119], v[184:187], v[192:195], v[116:119]
	v_mfma_f32_16x16x32_bf16 v[104:107], v[158:161], v[200:203], v[104:107]
	v_mfma_f32_16x16x32_bf16 v[100:103], v[184:187], v[200:203], v[100:103]
	v_mfma_f32_16x16x32_bf16 v[88:91], v[158:161], v[208:211], v[88:91]
	v_mfma_f32_16x16x32_bf16 v[84:87], v[184:187], v[208:211], v[84:87]
	v_mfma_f32_16x16x32_bf16 v[72:75], v[158:161], v[216:219], v[72:75]
	v_mfma_f32_16x16x32_bf16 v[68:71], v[184:187], v[216:219], v[68:71]
	v_mfma_f32_16x16x32_bf16 v[120:123], v[162:165], v[196:199], v[120:123]
	v_mfma_f32_16x16x32_bf16 v[116:119], v[188:191], v[196:199], v[116:119]
	v_mfma_f32_16x16x32_bf16 v[104:107], v[162:165], v[204:207], v[104:107]
	v_mfma_f32_16x16x32_bf16 v[100:103], v[188:191], v[204:207], v[100:103]
	v_mfma_f32_16x16x32_bf16 v[88:91], v[162:165], v[212:215], v[88:91]
	v_mfma_f32_16x16x32_bf16 v[84:87], v[188:191], v[212:215], v[84:87]
	v_mfma_f32_16x16x32_bf16 v[72:75], v[162:165], v[220:223], v[72:75]
	v_mfma_f32_16x16x32_bf16 v[68:71], v[188:191], v[220:223], v[68:71]
	s_barrier
	s_add_i32 s64, s64, s48
	v_lshl_add_u64 v[170:171], s[18:19], 0, v[174:175]
	s_mov_b32 m0, s64
	ds_read_b128 v[192:195], v169 offset:16384
	ds_read_b128 v[196:199], v169 offset:17408
	ds_read_b128 v[200:203], v169 offset:18432
	ds_read_b128 v[204:207], v169 offset:19456
	ds_read_b128 v[208:211], v169 offset:20480
	ds_read_b128 v[212:215], v169 offset:21504
	ds_read_b128 v[216:219], v169 offset:22528
	ds_read_b128 v[220:223], v169 offset:23552
	global_load_lds_dwordx4 v[170:171], off
	s_add_i32 m0, s64, 0x2000
	s_add_u32 s64, s18, 0x80000
	v_lshl_add_u64 v[224:225], s[18:19], 0, v[148:149]
	s_addc_u32 s65, s19, 0
	s_add_i32 s66, s66, s48
	global_load_lds_dwordx4 v[224:225], off
	v_lshl_add_u64 v[226:227], s[64:65], 0, v[174:175]
	s_mov_b32 m0, s66
	v_lshl_add_u64 v[228:229], s[26:27], 0, v[150:151]
	global_load_lds_dwordx4 v[226:227], off
	v_lshl_add_u64 v[226:227], s[64:65], 0, v[148:149]
	s_add_i32 m0, s66, 0x2000
	s_nop 0
	global_load_lds_dwordx4 v[226:227], off
	v_lshl_add_u64 v[226:227], s[26:27], 0, v[152:153]
	s_mov_b32 m0, s49
	s_nop 0
	global_load_lds_dwordx4 v[226:227], off
	s_mov_b32 m0, s50
	s_nop 0
	global_load_lds_dwordx4 v[228:229], off
	s_waitcnt vmcnt(8)
	s_waitcnt lgkmcnt(0)
	s_barrier
; #define PG8_STAGE(bufoff, gbase, voff) do { _Pragma("unroll") for (int _i = 0; _i < 2; ++_i) \
;         __builtin_amdgcn_global_load_lds((const unsigned*)((const char*)(gbase) + (voff)[_i]), (PG8_LAS unsigned*)(lds + (bufoff) + ldsw + _i * 8192), 16, 0, 0); } while (0)
; #define PG8_LDA(dst, b, h) do { _Pragma("unroll") for (int m = 0; m < 4; ++m) _Pragma("unroll") for (int k = 0; k < 2; ++k) dst[m][k] = *(const PG8_LAS bf16x8*)(lds + PG8_SA(b, h) + aoff + m * 2048 + k * 1024); } while (0)
; #define PG8_LDB(dst, b, h) do { _Pragma("unroll") for (int n = 0; n < 2; ++n) _Pragma("unroll") for (int k = 0; k < 2; ++k) dst[n][k] = *(const PG8_LAS bf16x8*)(lds + PG8_SB(b, h) + boff + n * 2048 + k * 1024); } while (0)
; #define PG8_MMA(ai, bj, At, Bt) do { __builtin_amdgcn_s_setprio(1); _Pragma("unroll") for (int m = 0; m < 4; ++m) _Pragma("unroll") for (int n = 0; n < 2; ++n) _Pragma("unroll") for (int k = 0; k < 2; ++k) \
;         acc[ai][bj][m][n] = __builtin_amdgcn_mfma_f32_16x16x32_bf16(Bt[n][k], At[m][k], acc[ai][bj][m][n], 0, 0, 0); __builtin_amdgcn_s_setprio(0); } while (0)
; #define PG8_WAIT_V(n) asm volatile("s_waitcnt vmcnt(" #n ")" ::: "memory")
; #define PG8_WAIT_L(n) asm volatile("s_waitcnt lgkmcnt(" #n ")" ::: "memory")
; #define PG8_BAR __builtin_amdgcn_s_barrier()
; #define PG8_SCHED __builtin_amdgcn_sched_barrier(0)
; template <class Epi, class Sched, bool ALIGN_EPI = false, bool SP2 = false>
; __device__ __forceinline__ void gemm_phase(PG8_LAS unsigned char* lds, const Gemm g, const Sched& S, const Epi& E) {
;     ...
;             PG8_LDA(At, 0, 1); PG8_STAGE(PG8_SB(0, 0), b2, voffB); PG8_STAGE(PG8_SB(0, 1), b2 + hstep, voffB); PG8_STAGE(PG8_SA(0, 0), a2, voffA);
;             PG8_WAIT_V(8); PG8_WAIT_L(0); PG8_BAR; PG8_MMA(1, 0, At, B0); PG8_MMA(1, 1, At, B1); PG8_BAR; PG8_SCHED;
;             PG8_LDB(B0, 1, 0); PG8_LDB(B1, 1, 1); PG8_SCHED; PG8_LDA(At, 1, 0); PG8_STAGE(PG8_SA(0, 1), a2 + hstep, voffA);
;             PG8_WAIT_V(8); PG8_WAIT_L(0); PG8_BAR; PG8_MMA(0, 0, At, B0); PG8_MMA(0, 1, At, B1); PG8_BAR; PG8_SCHED;
	v_mfma_f32_16x16x32_bf16 v[64:67], v[132:135], v[192:195], v[64:67]
	v_mfma_f32_16x16x32_bf16 v[60:63], v[140:143], v[192:195], v[60:63]
	v_mfma_f32_16x16x32_bf16 v[48:51], v[132:135], v[200:203], v[48:51]
	v_mfma_f32_16x16x32_bf16 v[44:47], v[140:143], v[200:203], v[44:47]
	v_mfma_f32_16x16x32_bf16 v[32:35], v[132:135], v[208:211], v[32:35]
	v_mfma_f32_16x16x32_bf16 v[28:31], v[140:143], v[208:211], v[28:31]
	v_mfma_f32_16x16x32_bf16 v[16:19], v[132:135], v[216:219], v[16:19]
	v_mfma_f32_16x16x32_bf16 v[12:15], v[140:143], v[216:219], v[12:15]
	v_mfma_f32_16x16x32_bf16 v[64:67], v[136:139], v[196:199], v[64:67]
	v_mfma_f32_16x16x32_bf16 v[60:63], v[144:147], v[196:199], v[60:63]
	v_mfma_f32_16x16x32_bf16 v[48:51], v[136:139], v[204:207], v[48:51]
	v_mfma_f32_16x16x32_bf16 v[44:47], v[144:147], v[204:207], v[44:47]
	v_mfma_f32_16x16x32_bf16 v[32:35], v[136:139], v[212:215], v[32:35]
	v_mfma_f32_16x16x32_bf16 v[28:31], v[144:147], v[212:215], v[28:31]
	v_mfma_f32_16x16x32_bf16 v[16:19], v[136:139], v[220:223], v[16:19]
	v_mfma_f32_16x16x32_bf16 v[12:15], v[144:147], v[220:223], v[12:15]
	v_mfma_f32_16x16x32_bf16 v[56:59], v[158:161], v[192:195], v[56:59]
	v_mfma_f32_16x16x32_bf16 v[52:55], v[184:187], v[192:195], v[52:55]
	v_mfma_f32_16x16x32_bf16 v[40:43], v[158:161], v[200:203], v[40:43]
	v_mfma_f32_16x16x32_bf16 v[36:39], v[184:187], v[200:203], v[36:39]
	v_mfma_f32_16x16x32_bf16 v[24:27], v[158:161], v[208:211], v[24:27]
	v_mfma_f32_16x16x32_bf16 v[20:23], v[184:187], v[208:211], v[20:23]
	v_mfma_f32_16x16x32_bf16 v[8:11], v[158:161], v[216:219], v[8:11]
	v_mfma_f32_16x16x32_bf16 v[4:7], v[184:187], v[216:219], v[4:7]
	v_mfma_f32_16x16x32_bf16 v[56:59], v[162:165], v[196:199], v[56:59]
	v_mfma_f32_16x16x32_bf16 v[52:55], v[188:191], v[196:199], v[52:55]
	v_mfma_f32_16x16x32_bf16 v[40:43], v[162:165], v[204:207], v[40:43]
	v_mfma_f32_16x16x32_bf16 v[36:39], v[188:191], v[204:207], v[36:39]
	v_mfma_f32_16x16x32_bf16 v[24:27], v[162:165], v[212:215], v[24:27]
	v_mfma_f32_16x16x32_bf16 v[20:23], v[188:191], v[212:215], v[20:23]
	v_mfma_f32_16x16x32_bf16 v[8:11], v[162:165], v[220:223], v[8:11]
	v_mfma_f32_16x16x32_bf16 v[4:7], v[188:191], v[220:223], v[4:7]
	s_barrier
	s_add_i32 s64, 0, 0x18000
	s_add_i32 s65, 0, 0x1c000
	v_add_u32_e32 v144, s64, v167
	v_add_u32_e32 v179, s65, v167
	ds_read_b128 v[132:135], v144
	ds_read_b128 v[136:139], v144 offset:1024
	ds_read_b128 v[140:143], v144 offset:2048
	ds_read_b128 v[144:147], v144 offset:3072
	ds_read_b128 v[158:161], v179
	ds_read_b128 v[162:165], v179 offset:1024
	ds_read_b128 v[184:187], v179 offset:2048
	ds_read_b128 v[188:191], v179 offset:3072
	s_add_u32 s26, s26, 0x80000
	s_addc_u32 s27, s27, 0
	s_mov_b32 m0, s51
	v_lshl_add_u64 v[230:231], s[26:27], 0, v[152:153]
	ds_read_b128 v[192:195], v169 offset:32768
	ds_read_b128 v[196:199], v169 offset:33792
	ds_read_b128 v[200:203], v169 offset:34816
	ds_read_b128 v[204:207], v169 offset:35840
	ds_read_b128 v[208:211], v169 offset:36864
	ds_read_b128 v[212:215], v169 offset:37888
	ds_read_b128 v[216:219], v169 offset:38912
	ds_read_b128 v[220:223], v169 offset:39936
	global_load_lds_dwordx4 v[230:231], off
	v_lshl_add_u64 v[230:231], s[26:27], 0, v[150:151]
	s_mov_b32 m0, s52
	s_nop 0
	global_load_lds_dwordx4 v[230:231], off
	s_waitcnt vmcnt(8)
	s_waitcnt lgkmcnt(0)
	s_barrier
	v_mfma_f32_16x16x32_bf16 v[128:131], v[132:135], v[192:195], v[128:131]
	v_mfma_f32_16x16x32_bf16 v[124:127], v[140:143], v[192:195], v[124:127]
	v_mfma_f32_16x16x32_bf16 v[112:115], v[132:135], v[200:203], v[112:115]
	v_mfma_f32_16x16x32_bf16 v[108:111], v[140:143], v[200:203], v[108:111]
	v_mfma_f32_16x16x32_bf16 v[96:99], v[132:135], v[208:211], v[96:99]
	v_mfma_f32_16x16x32_bf16 v[92:95], v[140:143], v[208:211], v[92:95]
	v_mfma_f32_16x16x32_bf16 v[80:83], v[132:135], v[216:219], v[80:83]
	v_mfma_f32_16x16x32_bf16 v[76:79], v[140:143], v[216:219], v[76:79]
	v_mfma_f32_16x16x32_bf16 v[128:131], v[136:139], v[196:199], v[128:131]
	v_mfma_f32_16x16x32_bf16 v[124:127], v[144:147], v[196:199], v[124:127]
	v_mfma_f32_16x16x32_bf16 v[112:115], v[136:139], v[204:207], v[112:115]
	v_mfma_f32_16x16x32_bf16 v[108:111], v[144:147], v[204:207], v[108:111]
	v_mfma_f32_16x16x32_bf16 v[96:99], v[136:139], v[212:215], v[96:99]
	v_mfma_f32_16x16x32_bf16 v[92:95], v[144:147], v[212:215], v[92:95]
	v_mfma_f32_16x16x32_bf16 v[80:83], v[136:139], v[220:223], v[80:83]
	v_mfma_f32_16x16x32_bf16 v[76:79], v[144:147], v[220:223], v[76:79]
	v_mfma_f32_16x16x32_bf16 v[120:123], v[158:161], v[192:195], v[120:123]
	v_mfma_f32_16x16x32_bf16 v[116:119], v[184:187], v[192:195], v[116:119]
	v_mfma_f32_16x16x32_bf16 v[104:107], v[158:161], v[200:203], v[104:107]
	v_mfma_f32_16x16x32_bf16 v[100:103], v[184:187], v[200:203], v[100:103]
	v_mfma_f32_16x16x32_bf16 v[88:91], v[158:161], v[208:211], v[88:91]
	v_mfma_f32_16x16x32_bf16 v[84:87], v[184:187], v[208:211], v[84:87]
	v_mfma_f32_16x16x32_bf16 v[72:75], v[158:161], v[216:219], v[72:75]
	v_mfma_f32_16x16x32_bf16 v[68:71], v[184:187], v[216:219], v[68:71]
	v_mfma_f32_16x16x32_bf16 v[120:123], v[162:165], v[196:199], v[120:123]
	v_mfma_f32_16x16x32_bf16 v[116:119], v[188:191], v[196:199], v[116:119]
	v_mfma_f32_16x16x32_bf16 v[104:107], v[162:165], v[204:207], v[104:107]
	v_mfma_f32_16x16x32_bf16 v[100:103], v[188:191], v[204:207], v[100:103]
	v_mfma_f32_16x16x32_bf16 v[88:91], v[162:165], v[212:215], v[88:91]
	v_mfma_f32_16x16x32_bf16 v[84:87], v[188:191], v[212:215], v[84:87]
	v_mfma_f32_16x16x32_bf16 v[72:75], v[162:165], v[220:223], v[72:75]
	v_mfma_f32_16x16x32_bf16 v[68:71], v[188:191], v[220:223], v[68:71]
	s_barrier
; #define PG8_STAGE(bufoff, gbase, voff) do { _Pragma("unroll") for (int _i = 0; _i < 2; ++_i) \
;         __builtin_amdgcn_global_load_lds((const unsigned*)((const char*)(gbase) + (voff)[_i]), (PG8_LAS unsigned*)(lds + (bufoff) + ldsw + _i * 8192), 16, 0, 0); } while (0)
; #define PG8_LDA(dst, b, h) do { _Pragma("unroll") for (int m = 0; m < 4; ++m) _Pragma("unroll") for (int k = 0; k < 2; ++k) dst[m][k] = *(const PG8_LAS bf16x8*)(lds + PG8_SA(b, h) + aoff + m * 2048 + k * 1024); } while (0)
; #define PG8_MMA(ai, bj, At, Bt) do { __builtin_amdgcn_s_setprio(1); _Pragma("unroll") for (int m = 0; m < 4; ++m) _Pragma("unroll") for (int n = 0; n < 2; ++n) _Pragma("unroll") for (int k = 0; k < 2; ++k) \
;         acc[ai][bj][m][n] = __builtin_amdgcn_mfma_f32_16x16x32_bf16(Bt[n][k], At[m][k], acc[ai][bj][m][n], 0, 0, 0); __builtin_amdgcn_s_setprio(0); } while (0)
; #define PG8_WAIT_V(n) asm volatile("s_waitcnt vmcnt(" #n ")" ::: "memory")
; #define PG8_WAIT_L(n) asm volatile("s_waitcnt lgkmcnt(" #n ")" ::: "memory")
; #define PG8_BAR __builtin_amdgcn_s_barrier()
; #define PG8_SCHED __builtin_amdgcn_sched_barrier(0)
; template <class Epi, class Sched, bool ALIGN_EPI = false, bool SP2 = false>
; __device__ __forceinline__ void gemm_phase(PG8_LAS unsigned char* lds, const Gemm g, const Sched& S, const Epi& E) {
;     ...
;             PG8_LDA(At, 1, 1); PG8_STAGE(PG8_SB(1, 0), b3, voffB); PG8_STAGE(PG8_SB(1, 1), b3 + hstep, voffB); PG8_STAGE(PG8_SA(1, 0), a3, voffA);
;             PG8_WAIT_V(8); PG8_WAIT_L(0); PG8_BAR; PG8_MMA(1, 0, At, B0); PG8_MMA(1, 1, At, B1); PG8_BAR; PG8_SCHED;
;     ...
;         if constexpr (ALIGN_EPI) { if (wr == 0) PG8_BAR; }
	s_add_i32 s26, s64, s48
	v_lshl_add_u64 v[170:171], v[170:171], 0, s[10:11]
	s_mov_b32 m0, s26
	ds_read_b128 v[192:195], v169 offset:49152
	ds_read_b128 v[196:199], v169 offset:50176
	ds_read_b128 v[200:203], v169 offset:51200
	ds_read_b128 v[204:207], v169 offset:52224
	ds_read_b128 v[208:211], v169 offset:53248
	ds_read_b128 v[212:215], v169 offset:54272
	ds_read_b128 v[216:219], v169 offset:55296
	ds_read_b128 v[220:223], v169 offset:56320
	global_load_lds_dwordx4 v[170:171], off
	s_add_i32 m0, s26, 0x2000
	s_add_u32 s18, s18, 0x80080
	v_lshl_add_u64 v[170:171], v[224:225], 0, s[10:11]
	s_addc_u32 s19, s19, 0
	s_add_i32 s26, s65, s48
	global_load_lds_dwordx4 v[170:171], off
	v_lshl_add_u64 v[170:171], s[18:19], 0, v[174:175]
	s_mov_b32 m0, s26
	s_nop 0
	global_load_lds_dwordx4 v[170:171], off
	v_lshl_add_u64 v[170:171], s[18:19], 0, v[148:149]
	s_add_i32 m0, s26, 0x2000
	s_nop 0
	global_load_lds_dwordx4 v[170:171], off
	v_lshl_add_u64 v[170:171], v[226:227], 0, s[10:11]
	s_mov_b32 m0, s54
	s_nop 0
	global_load_lds_dwordx4 v[170:171], off
	v_lshl_add_u64 v[170:171], v[228:229], 0, s[10:11]
	s_mov_b32 m0, s55
	s_nop 0
	global_load_lds_dwordx4 v[170:171], off
	s_waitcnt vmcnt(8)
	s_waitcnt lgkmcnt(0)
	s_barrier
	v_mfma_f32_16x16x32_bf16 v[64:67], v[132:135], v[192:195], v[64:67]
	v_mfma_f32_16x16x32_bf16 v[60:63], v[140:143], v[192:195], v[60:63]
	v_mfma_f32_16x16x32_bf16 v[48:51], v[132:135], v[200:203], v[48:51]
	v_mfma_f32_16x16x32_bf16 v[44:47], v[140:143], v[200:203], v[44:47]
	v_mfma_f32_16x16x32_bf16 v[32:35], v[132:135], v[208:211], v[32:35]
	v_mfma_f32_16x16x32_bf16 v[28:31], v[140:143], v[208:211], v[28:31]
	v_mfma_f32_16x16x32_bf16 v[16:19], v[132:135], v[216:219], v[16:19]
	v_mfma_f32_16x16x32_bf16 v[12:15], v[140:143], v[216:219], v[12:15]
	v_mfma_f32_16x16x32_bf16 v[64:67], v[136:139], v[196:199], v[64:67]
	v_mfma_f32_16x16x32_bf16 v[60:63], v[144:147], v[196:199], v[60:63]
	v_mfma_f32_16x16x32_bf16 v[48:51], v[136:139], v[204:207], v[48:51]
	v_mfma_f32_16x16x32_bf16 v[44:47], v[144:147], v[204:207], v[44:47]
	v_mfma_f32_16x16x32_bf16 v[32:35], v[136:139], v[212:215], v[32:35]
	v_mfma_f32_16x16x32_bf16 v[28:31], v[144:147], v[212:215], v[28:31]
	v_mfma_f32_16x16x32_bf16 v[16:19], v[136:139], v[220:223], v[16:19]
	v_mfma_f32_16x16x32_bf16 v[12:15], v[144:147], v[220:223], v[12:15]
	v_mfma_f32_16x16x32_bf16 v[56:59], v[158:161], v[192:195], v[56:59]
	v_mfma_f32_16x16x32_bf16 v[52:55], v[184:187], v[192:195], v[52:55]
	v_mfma_f32_16x16x32_bf16 v[40:43], v[158:161], v[200:203], v[40:43]
	v_mfma_f32_16x16x32_bf16 v[36:39], v[184:187], v[200:203], v[36:39]
	v_mfma_f32_16x16x32_bf16 v[24:27], v[158:161], v[208:211], v[24:27]
	v_mfma_f32_16x16x32_bf16 v[20:23], v[184:187], v[208:211], v[20:23]
	v_mfma_f32_16x16x32_bf16 v[8:11], v[158:161], v[216:219], v[8:11]
	v_mfma_f32_16x16x32_bf16 v[4:7], v[184:187], v[216:219], v[4:7]
	v_mfma_f32_16x16x32_bf16 v[56:59], v[162:165], v[196:199], v[56:59]
	v_mfma_f32_16x16x32_bf16 v[52:55], v[188:191], v[196:199], v[52:55]
	v_mfma_f32_16x16x32_bf16 v[40:43], v[162:165], v[204:207], v[40:43]
	v_mfma_f32_16x16x32_bf16 v[36:39], v[188:191], v[204:207], v[36:39]
	v_mfma_f32_16x16x32_bf16 v[24:27], v[162:165], v[212:215], v[24:27]
	v_mfma_f32_16x16x32_bf16 v[20:23], v[188:191], v[212:215], v[20:23]
	v_mfma_f32_16x16x32_bf16 v[8:11], v[162:165], v[220:223], v[8:11]
	v_mfma_f32_16x16x32_bf16 v[4:7], v[188:191], v[220:223], v[4:7]
	s_barrier
	s_add_i32 s63, s63, 2
	s_add_u32 s61, s61, 0x100
	s_addc_u32 s62, s62, 0
	s_add_u32 s0, s0, 0x100
	s_addc_u32 s1, s1, 0
	s_cmp_gt_u32 s63, 29
	s_cbranch_scc0 .LBB0_563
	s_and_b64 vcc, exec, s[34:35]
	s_cbranch_vccz .LBB0_566
	s_barrier

; #define PG8_STAGE(bufoff, gbase, voff) do { _Pragma("unroll") for (int _i = 0; _i < 2; ++_i) \
;         __builtin_amdgcn_global_load_lds((const unsigned*)((const char*)(gbase) + (voff)[_i]), (PG8_LAS unsigned*)(lds + (bufoff) + ldsw + _i * 8192), 16, 0, 0); } while (0)
; #define PG8_LDA(dst, b, h) do { _Pragma("unroll") for (int m = 0; m < 4; ++m) _Pragma("unroll") for (int k = 0; k < 2; ++k) dst[m][k] = *(const PG8_LAS bf16x8*)(lds + PG8_SA(b, h) + aoff + m * 2048 + k * 1024); } while (0)
; #define PG8_LDB(dst, b, h) do { _Pragma("unroll") for (int n = 0; n < 2; ++n) _Pragma("unroll") for (int k = 0; k < 2; ++k) dst[n][k] = *(const PG8_LAS bf16x8*)(lds + PG8_SB(b, h) + boff + n * 2048 + k * 1024); } while (0)
; #define PG8_MMA(ai, bj, At, Bt) do { __builtin_amdgcn_s_setprio(1); _Pragma("unroll") for (int m = 0; m < 4; ++m) _Pragma("unroll") for (int n = 0; n < 2; ++n) _Pragma("unroll") for (int k = 0; k < 2; ++k) \
;         acc[ai][bj][m][n] = __builtin_amdgcn_mfma_f32_16x16x32_bf16(Bt[n][k], At[m][k], acc[ai][bj][m][n], 0, 0, 0); __builtin_amdgcn_s_setprio(0); } while (0)
; #define PG8_WAIT_V(n) asm volatile("s_waitcnt vmcnt(" #n ")" ::: "memory")
; #define PG8_WAIT_L(n) asm volatile("s_waitcnt lgkmcnt(" #n ")" ::: "memory")
; #define PG8_BAR __builtin_amdgcn_s_barrier()
; template <class Epi, class Sched, bool ALIGN_EPI = false, bool SP2 = false>
; __device__ __forceinline__ void gemm_phase(PG8_LAS unsigned char* lds, const Gemm g, const Sched& S, const Epi& E) {
;     ...
;             const char* a1 = cA + (size_t)(t + 1) * kstep;
;             const char* a2 = last ? nA : cA + (size_t)(t + 2) * kstep; const char* b2 = last ? nB : cB + (size_t)(t + 2) * kstep;
;             const char* a3 = a2 + kstep; const char* b3 = b2 + kstep;
;             if (last && has_next) S.a_ready(nxt);
;             if constexpr (SP2) {
;             PG8_LDB(B0, 0, 0); PG8_LDB(B1, 0, 1); PG8_SCHED; PG8_LDA(At, 0, 0); PG8_STAGE(PG8_SA(1, 1), a1 + hstep, voffA);
;             PG8_WAIT_V(8); PG8_WAIT_L(0); PG8_BAR; PG8_MMA(0, 0, At, B0); PG8_MMA(0, 1, At, B1); PG8_BAR; PG8_SCHED;
;             PG8_LDA(At, 0, 1); PG8_STAGE(PG8_SB(0, 0), b2, voffB); PG8_STAGE(PG8_SB(0, 1), b2 + hstep, voffB); PG8_STAGE(PG8_SA(0, 0), a2, voffA);
;             PG8_WAIT_V(8); PG8_WAIT_L(0); PG8_BAR; PG8_MMA(1, 0, At, B0); PG8_MMA(1, 1, At, B1); PG8_BAR; PG8_SCHED;
.Lprio_done_660:
.LBB0_660:
	s_add_u32 s14, s0, 0xfff80080
	s_addc_u32 s15, s1, -1
	s_add_i32 s46, 0, 0x10000
	s_cmp_eq_u32 s45, 28
	s_cselect_b32 s17, s23, s15
	s_cselect_b32 s16, s24, s14
	s_cselect_b32 s15, s25, s44
	s_cselect_b32 s14, s42, s43
	s_add_i32 s63, 0, 0x14000
	v_add_u32_e32 v48, s46, v243
	v_add_u32_e32 v96, s63, v243
	ds_read_b128 v[36:39], v48
	ds_read_b128 v[40:43], v48 offset:1024
	ds_read_b128 v[44:47], v48 offset:2048
	ds_read_b128 v[48:51], v48 offset:3072
	ds_read_b128 v[76:79], v96
	ds_read_b128 v[80:83], v96 offset:1024
	ds_read_b128 v[84:87], v96 offset:2048
	ds_read_b128 v[96:99], v96 offset:3072
	v_lshl_add_u64 v[224:225], s[0:1], 0, v[198:199]
	s_add_i32 m0, s29, 0xc000
	ds_read_b128 v[164:167], v249
	ds_read_b128 v[168:171], v249 offset:1024
	ds_read_b128 v[200:203], v249 offset:2048
	ds_read_b128 v[204:207], v249 offset:3072
	ds_read_b128 v[208:211], v249 offset:4096
	ds_read_b128 v[212:215], v249 offset:5120
	ds_read_b128 v[216:219], v249 offset:6144
	ds_read_b128 v[220:223], v249 offset:7168
	global_load_lds_dwordx4 v[224:225], off
	v_lshl_add_u64 v[224:225], s[0:1], 0, v[196:197]
	s_add_i32 m0, s29, 0xe000
	s_nop 0
	global_load_lds_dwordx4 v[224:225], off
	s_waitcnt vmcnt(8)
	s_waitcnt lgkmcnt(0)
	s_barrier
	v_mfma_f32_16x16x32_bf16 v[152:155], v[36:39], v[164:167], v[152:155]
	v_mfma_f32_16x16x32_bf16 v[148:151], v[44:47], v[164:167], v[148:151]
	v_mfma_f32_16x16x32_bf16 v[136:139], v[36:39], v[200:203], v[136:139]
	v_mfma_f32_16x16x32_bf16 v[132:135], v[44:47], v[200:203], v[132:135]
	v_mfma_f32_16x16x32_bf16 v[128:131], v[36:39], v[208:211], v[128:131]
	v_mfma_f32_16x16x32_bf16 v[124:127], v[44:47], v[208:211], v[124:127]
	v_mfma_f32_16x16x32_bf16 v[160:163], v[36:39], v[216:219], v[160:163]
	v_mfma_f32_16x16x32_bf16 v[156:159], v[44:47], v[216:219], v[156:159]
	v_mfma_f32_16x16x32_bf16 v[152:155], v[40:43], v[168:171], v[152:155]
	v_mfma_f32_16x16x32_bf16 v[148:151], v[48:51], v[168:171], v[148:151]
	v_mfma_f32_16x16x32_bf16 v[136:139], v[40:43], v[204:207], v[136:139]
	v_mfma_f32_16x16x32_bf16 v[132:135], v[48:51], v[204:207], v[132:135]
	v_mfma_f32_16x16x32_bf16 v[128:131], v[40:43], v[212:215], v[128:131]
	v_mfma_f32_16x16x32_bf16 v[124:127], v[48:51], v[212:215], v[124:127]
	v_mfma_f32_16x16x32_bf16 v[160:163], v[40:43], v[220:223], v[160:163]
	v_mfma_f32_16x16x32_bf16 v[156:159], v[48:51], v[220:223], v[156:159]
	v_mfma_f32_16x16x32_bf16 v[144:147], v[76:79], v[164:167], v[144:147]
	v_mfma_f32_16x16x32_bf16 v[140:143], v[84:87], v[164:167], v[140:143]
	v_mfma_f32_16x16x32_bf16 v[120:123], v[76:79], v[200:203], v[120:123]
	v_mfma_f32_16x16x32_bf16 v[116:119], v[84:87], v[200:203], v[116:119]
	v_mfma_f32_16x16x32_bf16 v[112:115], v[76:79], v[208:211], v[112:115]
	v_mfma_f32_16x16x32_bf16 v[108:111], v[84:87], v[208:211], v[108:111]
	v_mfma_f32_16x16x32_bf16 v[104:107], v[76:79], v[216:219], v[104:107]
	v_mfma_f32_16x16x32_bf16 v[100:103], v[84:87], v[216:219], v[100:103]
	v_mfma_f32_16x16x32_bf16 v[144:147], v[80:83], v[168:171], v[144:147]
	v_mfma_f32_16x16x32_bf16 v[140:143], v[96:99], v[168:171], v[140:143]
	v_mfma_f32_16x16x32_bf16 v[120:123], v[80:83], v[204:207], v[120:123]
	v_mfma_f32_16x16x32_bf16 v[116:119], v[96:99], v[204:207], v[116:119]
	v_mfma_f32_16x16x32_bf16 v[112:115], v[80:83], v[212:215], v[112:115]
	v_mfma_f32_16x16x32_bf16 v[108:111], v[96:99], v[212:215], v[108:111]
	v_mfma_f32_16x16x32_bf16 v[104:107], v[80:83], v[220:223], v[104:107]
	v_mfma_f32_16x16x32_bf16 v[100:103], v[96:99], v[220:223], v[100:103]
	s_barrier
	s_add_i32 s46, s46, s28
	v_lshl_add_u64 v[232:233], s[14:15], 0, v[188:189]
	s_mov_b32 m0, s46
	ds_read_b128 v[164:167], v249 offset:16384
	ds_read_b128 v[168:171], v249 offset:17408
	ds_read_b128 v[200:203], v249 offset:18432
	ds_read_b128 v[204:207], v249 offset:19456
	ds_read_b128 v[208:211], v249 offset:20480
	ds_read_b128 v[212:215], v249 offset:21504
	ds_read_b128 v[216:219], v249 offset:22528
	ds_read_b128 v[220:223], v249 offset:23552
	global_load_lds_dwordx4 v[232:233], off
	s_add_i32 m0, s46, 0x2000
	s_add_u32 s46, s14, 0x80000
	v_lshl_add_u64 v[234:235], s[14:15], 0, v[184:185]
	s_addc_u32 s47, s15, 0
	s_add_i32 s63, s63, s28
	global_load_lds_dwordx4 v[234:235], off
	v_lshl_add_u64 v[224:225], s[46:47], 0, v[188:189]
	s_mov_b32 m0, s63
	v_lshl_add_u64 v[236:237], s[16:17], 0, v[190:191]
	global_load_lds_dwordx4 v[224:225], off
	v_lshl_add_u64 v[224:225], s[46:47], 0, v[184:185]
	s_add_i32 m0, s63, 0x2000
	v_lshl_add_u64 v[250:251], s[16:17], 0, v[186:187]
	global_load_lds_dwordx4 v[224:225], off
	s_mov_b32 m0, s29
	s_nop 0
	global_load_lds_dwordx4 v[236:237], off
	s_mov_b32 m0, s30
	s_nop 0
	global_load_lds_dwordx4 v[250:251], off
	s_waitcnt vmcnt(8)
	s_waitcnt lgkmcnt(0)
	s_barrier
; #define PG8_STAGE(bufoff, gbase, voff) do { _Pragma("unroll") for (int _i = 0; _i < 2; ++_i) \
;         __builtin_amdgcn_global_load_lds((const unsigned*)((const char*)(gbase) + (voff)[_i]), (PG8_LAS unsigned*)(lds + (bufoff) + ldsw + _i * 8192), 16, 0, 0); } while (0)
; #define PG8_LDA(dst, b, h) do { _Pragma("unroll") for (int m = 0; m < 4; ++m) _Pragma("unroll") for (int k = 0; k < 2; ++k) dst[m][k] = *(const PG8_LAS bf16x8*)(lds + PG8_SA(b, h) + aoff + m * 2048 + k * 1024); } while (0)
; #define PG8_LDB(dst, b, h) do { _Pragma("unroll") for (int n = 0; n < 2; ++n) _Pragma("unroll") for (int k = 0; k < 2; ++k) dst[n][k] = *(const PG8_LAS bf16x8*)(lds + PG8_SB(b, h) + boff + n * 2048 + k * 1024); } while (0)
; #define PG8_MMA(ai, bj, At, Bt) do { __builtin_amdgcn_s_setprio(1); _Pragma("unroll") for (int m = 0; m < 4; ++m) _Pragma("unroll") for (int n = 0; n < 2; ++n) _Pragma("unroll") for (int k = 0; k < 2; ++k) \
;         acc[ai][bj][m][n] = __builtin_amdgcn_mfma_f32_16x16x32_bf16(Bt[n][k], At[m][k], acc[ai][bj][m][n], 0, 0, 0); __builtin_amdgcn_s_setprio(0); } while (0)
; #define PG8_WAIT_V(n) asm volatile("s_waitcnt vmcnt(" #n ")" ::: "memory")
; #define PG8_WAIT_L(n) asm volatile("s_waitcnt lgkmcnt(" #n ")" ::: "memory")
; #define PG8_BAR __builtin_amdgcn_s_barrier()
; #define PG8_SCHED __builtin_amdgcn_sched_barrier(0)
; template <class Epi, class Sched, bool ALIGN_EPI = false, bool SP2 = false>
; __device__ __forceinline__ void gemm_phase(PG8_LAS unsigned char* lds, const Gemm g, const Sched& S, const Epi& E) {
;     ...
;             PG8_LDA(At, 0, 1); PG8_STAGE(PG8_SB(0, 0), b2, voffB); PG8_STAGE(PG8_SB(0, 1), b2 + hstep, voffB); PG8_STAGE(PG8_SA(0, 0), a2, voffA);
;             PG8_WAIT_V(8); PG8_WAIT_L(0); PG8_BAR; PG8_MMA(1, 0, At, B0); PG8_MMA(1, 1, At, B1); PG8_BAR; PG8_SCHED;
;             PG8_LDB(B0, 1, 0); PG8_LDB(B1, 1, 1); PG8_SCHED; PG8_LDA(At, 1, 0); PG8_STAGE(PG8_SA(0, 1), a2 + hstep, voffA);
;             PG8_WAIT_V(8); PG8_WAIT_L(0); PG8_BAR; PG8_MMA(0, 0, At, B0); PG8_MMA(0, 1, At, B1); PG8_BAR; PG8_SCHED;
	v_mfma_f32_16x16x32_bf16 v[72:75], v[36:39], v[164:167], v[72:75]
	v_mfma_f32_16x16x32_bf16 v[68:71], v[44:47], v[164:167], v[68:71]
	v_mfma_f32_16x16x32_bf16 v[64:67], v[36:39], v[200:203], v[64:67]
	v_mfma_f32_16x16x32_bf16 v[60:63], v[44:47], v[200:203], v[60:63]
	v_mfma_f32_16x16x32_bf16 v[56:59], v[36:39], v[208:211], v[56:59]
	v_mfma_f32_16x16x32_bf16 v[52:55], v[44:47], v[208:211], v[52:55]
	v_mfma_f32_16x16x32_bf16 v[36:39], v[36:39], v[216:219], v[92:95]
	v_mfma_f32_16x16x32_bf16 v[72:75], v[40:43], v[168:171], v[72:75]
	v_mfma_f32_16x16x32_bf16 v[68:71], v[48:51], v[168:171], v[68:71]
	v_mfma_f32_16x16x32_bf16 v[64:67], v[40:43], v[204:207], v[64:67]
	v_mfma_f32_16x16x32_bf16 v[60:63], v[48:51], v[204:207], v[60:63]
	v_mfma_f32_16x16x32_bf16 v[56:59], v[40:43], v[212:215], v[56:59]
	v_mfma_f32_16x16x32_bf16 v[52:55], v[48:51], v[212:215], v[52:55]
	v_mfma_f32_16x16x32_bf16 v[36:39], v[40:43], v[220:223], v[36:39]
	v_mfma_f32_16x16x32_bf16 v[40:43], v[44:47], v[216:219], v[88:91]
	v_mfma_f32_16x16x32_bf16 v[40:43], v[48:51], v[220:223], v[40:43]
	v_mfma_f32_16x16x32_bf16 v[32:35], v[76:79], v[164:167], v[32:35]
	v_mfma_f32_16x16x32_bf16 v[28:31], v[84:87], v[164:167], v[28:31]
	v_mfma_f32_16x16x32_bf16 v[24:27], v[76:79], v[200:203], v[24:27]
	v_mfma_f32_16x16x32_bf16 v[20:23], v[84:87], v[200:203], v[20:23]
	v_mfma_f32_16x16x32_bf16 v[16:19], v[76:79], v[208:211], v[16:19]
	v_mfma_f32_16x16x32_bf16 v[12:15], v[84:87], v[208:211], v[12:15]
	v_mfma_f32_16x16x32_bf16 v[8:11], v[76:79], v[216:219], v[8:11]
	v_mfma_f32_16x16x32_bf16 v[4:7], v[84:87], v[216:219], v[4:7]
	v_mfma_f32_16x16x32_bf16 v[32:35], v[80:83], v[168:171], v[32:35]
	v_mfma_f32_16x16x32_bf16 v[28:31], v[96:99], v[168:171], v[28:31]
	v_mfma_f32_16x16x32_bf16 v[24:27], v[80:83], v[204:207], v[24:27]
	v_mfma_f32_16x16x32_bf16 v[20:23], v[96:99], v[204:207], v[20:23]
	v_mfma_f32_16x16x32_bf16 v[16:19], v[80:83], v[212:215], v[16:19]
	v_mfma_f32_16x16x32_bf16 v[12:15], v[96:99], v[212:215], v[12:15]
	v_mfma_f32_16x16x32_bf16 v[8:11], v[80:83], v[220:223], v[8:11]
	v_mfma_f32_16x16x32_bf16 v[4:7], v[96:99], v[220:223], v[4:7]
	s_barrier
	s_add_i32 s46, 0, 0x18000
	s_add_i32 s47, 0, 0x1c000
	v_add_u32_e32 v80, s46, v243
	v_add_u32_e32 v88, s47, v243
	ds_read_b128 v[44:47], v80
	ds_read_b128 v[48:51], v80 offset:1024
	ds_read_b128 v[76:79], v80 offset:2048
	ds_read_b128 v[80:83], v80 offset:3072
	ds_read_b128 v[84:87], v88
	ds_read_b128 v[96:99], v88 offset:1024
	ds_read_b128 v[164:167], v88 offset:2048
	ds_read_b128 v[168:171], v88 offset:3072
	s_add_u32 s16, s16, 0x80000
	s_addc_u32 s17, s17, 0
	s_mov_b32 m0, s31
	v_lshl_add_u64 v[224:225], s[16:17], 0, v[190:191]
	ds_read_b128 v[88:91], v249 offset:32768
	ds_read_b128 v[92:95], v249 offset:33792
	ds_read_b128 v[200:203], v249 offset:34816
	ds_read_b128 v[204:207], v249 offset:35840
	ds_read_b128 v[208:211], v249 offset:36864
	ds_read_b128 v[212:215], v249 offset:37888
	ds_read_b128 v[216:219], v249 offset:38912
	ds_read_b128 v[220:223], v249 offset:39936
	global_load_lds_dwordx4 v[224:225], off
	v_lshl_add_u64 v[224:225], s[16:17], 0, v[186:187]
	s_mov_b32 m0, s34
	s_nop 0
	global_load_lds_dwordx4 v[224:225], off
	s_waitcnt vmcnt(8)
	s_waitcnt lgkmcnt(0)
	s_barrier
	v_mfma_f32_16x16x32_bf16 v[152:155], v[44:47], v[88:91], v[152:155]
	v_mfma_f32_16x16x32_bf16 v[148:151], v[76:79], v[88:91], v[148:151]
	v_mfma_f32_16x16x32_bf16 v[136:139], v[44:47], v[200:203], v[136:139]
	v_mfma_f32_16x16x32_bf16 v[132:135], v[76:79], v[200:203], v[132:135]
	v_mfma_f32_16x16x32_bf16 v[128:131], v[44:47], v[208:211], v[128:131]
	v_mfma_f32_16x16x32_bf16 v[124:127], v[76:79], v[208:211], v[124:127]
	v_mfma_f32_16x16x32_bf16 v[160:163], v[44:47], v[216:219], v[160:163]
	v_mfma_f32_16x16x32_bf16 v[156:159], v[76:79], v[216:219], v[156:159]
	v_mfma_f32_16x16x32_bf16 v[152:155], v[48:51], v[92:95], v[152:155]
	v_mfma_f32_16x16x32_bf16 v[148:151], v[80:83], v[92:95], v[148:151]
	v_mfma_f32_16x16x32_bf16 v[136:139], v[48:51], v[204:207], v[136:139]
	v_mfma_f32_16x16x32_bf16 v[132:135], v[80:83], v[204:207], v[132:135]
	v_mfma_f32_16x16x32_bf16 v[128:131], v[48:51], v[212:215], v[128:131]
	v_mfma_f32_16x16x32_bf16 v[124:127], v[80:83], v[212:215], v[124:127]
	v_mfma_f32_16x16x32_bf16 v[160:163], v[48:51], v[220:223], v[160:163]
	v_mfma_f32_16x16x32_bf16 v[156:159], v[80:83], v[220:223], v[156:159]
	v_mfma_f32_16x16x32_bf16 v[144:147], v[84:87], v[88:91], v[144:147]
	v_mfma_f32_16x16x32_bf16 v[88:91], v[164:167], v[88:91], v[140:143]
	v_mfma_f32_16x16x32_bf16 v[140:143], v[168:171], v[92:95], v[88:91]
	v_mfma_f32_16x16x32_bf16 v[88:91], v[84:87], v[200:203], v[120:123]
	v_mfma_f32_16x16x32_bf16 v[120:123], v[96:99], v[204:207], v[88:91]
	v_mfma_f32_16x16x32_bf16 v[88:91], v[164:167], v[200:203], v[116:119]
	v_mfma_f32_16x16x32_bf16 v[116:119], v[168:171], v[204:207], v[88:91]
	v_mfma_f32_16x16x32_bf16 v[88:91], v[84:87], v[208:211], v[112:115]
	v_mfma_f32_16x16x32_bf16 v[112:115], v[96:99], v[212:215], v[88:91]
	v_mfma_f32_16x16x32_bf16 v[88:91], v[164:167], v[208:211], v[108:111]
	v_mfma_f32_16x16x32_bf16 v[108:111], v[168:171], v[212:215], v[88:91]
	v_mfma_f32_16x16x32_bf16 v[88:91], v[84:87], v[216:219], v[104:107]
	v_mfma_f32_16x16x32_bf16 v[104:107], v[96:99], v[220:223], v[88:91]
	v_mfma_f32_16x16x32_bf16 v[88:91], v[164:167], v[216:219], v[100:103]
	v_mfma_f32_16x16x32_bf16 v[144:147], v[96:99], v[92:95], v[144:147]
	v_mfma_f32_16x16x32_bf16 v[100:103], v[168:171], v[220:223], v[88:91]
	s_barrier
; #define PG8_STAGE(bufoff, gbase, voff) do { _Pragma("unroll") for (int _i = 0; _i < 2; ++_i) \
;         __builtin_amdgcn_global_load_lds((const unsigned*)((const char*)(gbase) + (voff)[_i]), (PG8_LAS unsigned*)(lds + (bufoff) + ldsw + _i * 8192), 16, 0, 0); } while (0)
; #define PG8_LDA(dst, b, h) do { _Pragma("unroll") for (int m = 0; m < 4; ++m) _Pragma("unroll") for (int k = 0; k < 2; ++k) dst[m][k] = *(const PG8_LAS bf16x8*)(lds + PG8_SA(b, h) + aoff + m * 2048 + k * 1024); } while (0)
; #define PG8_MMA(ai, bj, At, Bt) do { __builtin_amdgcn_s_setprio(1); _Pragma("unroll") for (int m = 0; m < 4; ++m) _Pragma("unroll") for (int n = 0; n < 2; ++n) _Pragma("unroll") for (int k = 0; k < 2; ++k) \
;         acc[ai][bj][m][n] = __builtin_amdgcn_mfma_f32_16x16x32_bf16(Bt[n][k], At[m][k], acc[ai][bj][m][n], 0, 0, 0); __builtin_amdgcn_s_setprio(0); } while (0)
; #define PG8_WAIT_V(n) asm volatile("s_waitcnt vmcnt(" #n ")" ::: "memory")
; #define PG8_WAIT_L(n) asm volatile("s_waitcnt lgkmcnt(" #n ")" ::: "memory")
; #define PG8_BAR __builtin_amdgcn_s_barrier()
; #define PG8_SCHED __builtin_amdgcn_sched_barrier(0)
; template <class Epi, class Sched, bool ALIGN_EPI = false, bool SP2 = false>
; __device__ __forceinline__ void gemm_phase(PG8_LAS unsigned char* lds, const Gemm g, const Sched& S, const Epi& E) {
;     ...
;             PG8_LDA(At, 1, 1); PG8_STAGE(PG8_SB(1, 0), b3, voffB); PG8_STAGE(PG8_SB(1, 1), b3 + hstep, voffB); PG8_STAGE(PG8_SA(1, 0), a3, voffA);
;             PG8_WAIT_V(8); PG8_WAIT_L(0); PG8_BAR; PG8_MMA(1, 0, At, B0); PG8_MMA(1, 1, At, B1); PG8_BAR; PG8_SCHED;
;     ...
;         if constexpr (ALIGN_EPI) { if (wr == 0) PG8_BAR; }
	s_add_i32 s16, s46, s28
	s_nop 2
	v_lshl_add_u64 v[88:89], v[232:233], 0, s[10:11]
	s_mov_b32 m0, s16
	ds_read_b128 v[200:203], v249 offset:49152
	ds_read_b128 v[204:207], v249 offset:50176
	ds_read_b128 v[208:211], v249 offset:51200
	ds_read_b128 v[212:215], v249 offset:52224
	ds_read_b128 v[216:219], v249 offset:53248
	ds_read_b128 v[220:223], v249 offset:54272
	ds_read_b128 v[224:227], v249 offset:55296
	ds_read_b128 v[228:231], v249 offset:56320
	global_load_lds_dwordx4 v[88:89], off
	s_add_i32 m0, s16, 0x2000
	s_add_u32 s14, s14, 0x80080
	v_lshl_add_u64 v[88:89], v[234:235], 0, s[10:11]
	s_addc_u32 s15, s15, 0
	s_add_i32 s16, s47, s28
	global_load_lds_dwordx4 v[88:89], off
	v_lshl_add_u64 v[88:89], s[14:15], 0, v[188:189]
	s_mov_b32 m0, s16
	s_nop 0
	global_load_lds_dwordx4 v[88:89], off
	v_lshl_add_u64 v[88:89], s[14:15], 0, v[184:185]
	s_add_i32 m0, s16, 0x2000
	s_nop 0
	global_load_lds_dwordx4 v[88:89], off
	v_lshl_add_u64 v[88:89], v[236:237], 0, s[10:11]
	s_mov_b32 m0, s72
	s_nop 0
	global_load_lds_dwordx4 v[88:89], off
	v_lshl_add_u64 v[88:89], v[250:251], 0, s[10:11]
	s_mov_b32 m0, s73
	s_nop 0
	global_load_lds_dwordx4 v[88:89], off
	s_waitcnt vmcnt(8)
	s_waitcnt lgkmcnt(0)
	s_barrier
	v_mfma_f32_16x16x32_bf16 v[36:39], v[44:47], v[224:227], v[36:39]
	v_mfma_f32_16x16x32_bf16 v[72:75], v[44:47], v[200:203], v[72:75]
	v_mfma_f32_16x16x32_bf16 v[68:71], v[76:79], v[200:203], v[68:71]
	v_mfma_f32_16x16x32_bf16 v[64:67], v[44:47], v[208:211], v[64:67]
	v_mfma_f32_16x16x32_bf16 v[60:63], v[76:79], v[208:211], v[60:63]
	v_mfma_f32_16x16x32_bf16 v[56:59], v[44:47], v[216:219], v[56:59]
	v_mfma_f32_16x16x32_bf16 v[52:55], v[76:79], v[216:219], v[52:55]
	v_mfma_f32_16x16x32_bf16 v[92:95], v[48:51], v[228:231], v[36:39]
	v_mfma_f32_16x16x32_bf16 v[36:39], v[76:79], v[224:227], v[40:43]
	v_mfma_f32_16x16x32_bf16 v[72:75], v[48:51], v[204:207], v[72:75]
	v_mfma_f32_16x16x32_bf16 v[68:71], v[80:83], v[204:207], v[68:71]
	v_mfma_f32_16x16x32_bf16 v[64:67], v[48:51], v[212:215], v[64:67]
	v_mfma_f32_16x16x32_bf16 v[60:63], v[80:83], v[212:215], v[60:63]
	v_mfma_f32_16x16x32_bf16 v[56:59], v[48:51], v[220:223], v[56:59]
	v_mfma_f32_16x16x32_bf16 v[52:55], v[80:83], v[220:223], v[52:55]
	v_mfma_f32_16x16x32_bf16 v[88:91], v[80:83], v[228:231], v[36:39]
	v_mfma_f32_16x16x32_bf16 v[32:35], v[84:87], v[200:203], v[32:35]
	v_mfma_f32_16x16x32_bf16 v[28:31], v[164:167], v[200:203], v[28:31]
	v_mfma_f32_16x16x32_bf16 v[24:27], v[84:87], v[208:211], v[24:27]
	v_mfma_f32_16x16x32_bf16 v[20:23], v[164:167], v[208:211], v[20:23]
	v_mfma_f32_16x16x32_bf16 v[16:19], v[84:87], v[216:219], v[16:19]
	v_mfma_f32_16x16x32_bf16 v[12:15], v[164:167], v[216:219], v[12:15]
	v_mfma_f32_16x16x32_bf16 v[8:11], v[84:87], v[224:227], v[8:11]
	v_mfma_f32_16x16x32_bf16 v[4:7], v[164:167], v[224:227], v[4:7]
	v_mfma_f32_16x16x32_bf16 v[32:35], v[96:99], v[204:207], v[32:35]
	v_mfma_f32_16x16x32_bf16 v[28:31], v[168:171], v[204:207], v[28:31]
	v_mfma_f32_16x16x32_bf16 v[24:27], v[96:99], v[212:215], v[24:27]
	v_mfma_f32_16x16x32_bf16 v[20:23], v[168:171], v[212:215], v[20:23]
	v_mfma_f32_16x16x32_bf16 v[16:19], v[96:99], v[220:223], v[16:19]
	v_mfma_f32_16x16x32_bf16 v[12:15], v[168:171], v[220:223], v[12:15]
	v_mfma_f32_16x16x32_bf16 v[8:11], v[96:99], v[228:231], v[8:11]
	v_mfma_f32_16x16x32_bf16 v[4:7], v[168:171], v[228:231], v[4:7]
	s_barrier
	s_add_i32 s45, s45, 2
	s_add_u32 s43, s43, 0x100
	s_addc_u32 s44, s44, 0
	s_add_u32 s0, s0, 0x100
	s_addc_u32 s1, s1, 0
	s_cmp_gt_u32 s45, 29
	s_cbranch_scc0 .LBB0_660
	s_and_b64 vcc, exec, s[52:53]
	s_cbranch_vccz .LBB0_663
	s_barrier

; #define PG8_STAGE(bufoff, gbase, voff) do { _Pragma("unroll") for (int _i = 0; _i < 2; ++_i) \
;         __builtin_amdgcn_global_load_lds((const unsigned*)((const char*)(gbase) + (voff)[_i]), (PG8_LAS unsigned*)(lds + (bufoff) + ldsw + _i * 8192), 16, 0, 0); } while (0)
; #define PG8_LDA(dst, b, h) do { _Pragma("unroll") for (int m = 0; m < 4; ++m) _Pragma("unroll") for (int k = 0; k < 2; ++k) dst[m][k] = *(const PG8_LAS bf16x8*)(lds + PG8_SA(b, h) + aoff + m * 2048 + k * 1024); } while (0)
; #define PG8_LDB(dst, b, h) do { _Pragma("unroll") for (int n = 0; n < 2; ++n) _Pragma("unroll") for (int k = 0; k < 2; ++k) dst[n][k] = *(const PG8_LAS bf16x8*)(lds + PG8_SB(b, h) + boff + n * 2048 + k * 1024); } while (0)
; #define PG8_MMA(ai, bj, At, Bt) do { __builtin_amdgcn_s_setprio(1); _Pragma("unroll") for (int m = 0; m < 4; ++m) _Pragma("unroll") for (int n = 0; n < 2; ++n) _Pragma("unroll") for (int k = 0; k < 2; ++k) \
;         acc[ai][bj][m][n] = __builtin_amdgcn_mfma_f32_16x16x32_bf16(Bt[n][k], At[m][k], acc[ai][bj][m][n], 0, 0, 0); __builtin_amdgcn_s_setprio(0); } while (0)
; #define PG8_WAIT_V(n) asm volatile("s_waitcnt vmcnt(" #n ")" ::: "memory")
; #define PG8_WAIT_L(n) asm volatile("s_waitcnt lgkmcnt(" #n ")" ::: "memory")
; #define PG8_BAR __builtin_amdgcn_s_barrier()
; template <class Epi, class Sched, bool ALIGN_EPI = false, bool SP2 = false>
; __device__ __forceinline__ void gemm_phase(PG8_LAS unsigned char* lds, const Gemm g, const Sched& S, const Epi& E) {
;     ...
;             const char* a1 = cA + (size_t)(t + 1) * kstep;
;             const char* a2 = last ? nA : cA + (size_t)(t + 2) * kstep; const char* b2 = last ? nB : cB + (size_t)(t + 2) * kstep;
;             const char* a3 = a2 + kstep; const char* b3 = b2 + kstep;
;             if (last && has_next) S.a_ready(nxt);
;             if constexpr (SP2) {
;             PG8_LDB(B0, 0, 0); PG8_LDB(B1, 0, 1); PG8_SCHED; PG8_LDA(At, 0, 0); PG8_STAGE(PG8_SA(1, 1), a1 + hstep, voffA);
;             PG8_WAIT_V(8); PG8_WAIT_L(0); PG8_BAR; PG8_MMA(0, 0, At, B0); PG8_MMA(0, 1, At, B1); PG8_BAR; PG8_SCHED;
;             PG8_LDA(At, 0, 1); PG8_STAGE(PG8_SB(0, 0), b2, voffB); PG8_STAGE(PG8_SB(0, 1), b2 + hstep, voffB); PG8_STAGE(PG8_SA(0, 0), a2, voffA);
;             PG8_WAIT_V(8); PG8_WAIT_L(0); PG8_BAR; PG8_MMA(1, 0, At, B0); PG8_MMA(1, 1, At, B1); PG8_BAR; PG8_SCHED;
.Lprio_done_822:
.LBB0_822:
	s_add_u32 s14, s0, 0x100
	s_addc_u32 s15, s1, 0
	s_add_i32 s60, 0, 0x10000
	s_cmpk_eq_i32 s25, 0x52
	s_cselect_b32 s19, s41, s15
	s_cselect_b32 s18, s40, s14
	s_cselect_b32 s17, s51, s24
	s_cselect_b32 s16, s50, s23
	s_add_i32 s61, 0, 0x14000
	v_add_u32_e32 v154, s60, v159
	v_add_u32_e32 v170, s61, v159
	ds_read_b128 v[116:119], v154
	ds_read_b128 v[120:123], v154 offset:1024
	ds_read_b128 v[150:153], v154 offset:2048
	ds_read_b128 v[154:157], v154 offset:3072
	ds_read_b128 v[162:165], v170
	ds_read_b128 v[166:169], v170 offset:1024
	ds_read_b128 v[184:187], v170 offset:2048
	ds_read_b128 v[188:191], v170 offset:3072
	v_lshl_add_u64 v[170:171], s[0:1], 0, v[148:149]
	s_add_i32 m0, s31, 0xc000
	ds_read_b128 v[192:195], v161
	ds_read_b128 v[196:199], v161 offset:1024
	ds_read_b128 v[200:203], v161 offset:2048
	ds_read_b128 v[204:207], v161 offset:3072
	ds_read_b128 v[208:211], v161 offset:4096
	ds_read_b128 v[212:215], v161 offset:5120
	ds_read_b128 v[216:219], v161 offset:6144
	ds_read_b128 v[220:223], v161 offset:7168
	global_load_lds_dwordx4 v[170:171], off
	v_lshl_add_u64 v[170:171], s[0:1], 0, v[146:147]
	s_add_i32 m0, s31, 0xe000
	s_nop 0
	global_load_lds_dwordx4 v[170:171], off
	s_waitcnt vmcnt(8)
	s_waitcnt lgkmcnt(0)
	s_barrier
	v_mfma_f32_16x16x32_bf16 v[136:139], v[116:119], v[192:195], v[136:139]
	v_mfma_f32_16x16x32_bf16 v[132:135], v[150:153], v[192:195], v[132:135]
	v_mfma_f32_16x16x32_bf16 v[112:115], v[116:119], v[200:203], v[112:115]
	v_mfma_f32_16x16x32_bf16 v[108:111], v[150:153], v[200:203], v[108:111]
	v_mfma_f32_16x16x32_bf16 v[96:99], v[116:119], v[208:211], v[96:99]
	v_mfma_f32_16x16x32_bf16 v[92:95], v[150:153], v[208:211], v[92:95]
	v_mfma_f32_16x16x32_bf16 v[80:83], v[116:119], v[216:219], v[80:83]
	v_mfma_f32_16x16x32_bf16 v[76:79], v[150:153], v[216:219], v[76:79]
	v_mfma_f32_16x16x32_bf16 v[136:139], v[120:123], v[196:199], v[136:139]
	v_mfma_f32_16x16x32_bf16 v[132:135], v[154:157], v[196:199], v[132:135]
	v_mfma_f32_16x16x32_bf16 v[112:115], v[120:123], v[204:207], v[112:115]
	v_mfma_f32_16x16x32_bf16 v[108:111], v[154:157], v[204:207], v[108:111]
	v_mfma_f32_16x16x32_bf16 v[96:99], v[120:123], v[212:215], v[96:99]
	v_mfma_f32_16x16x32_bf16 v[92:95], v[154:157], v[212:215], v[92:95]
	v_mfma_f32_16x16x32_bf16 v[80:83], v[120:123], v[220:223], v[80:83]
	v_mfma_f32_16x16x32_bf16 v[76:79], v[154:157], v[220:223], v[76:79]
	v_mfma_f32_16x16x32_bf16 v[128:131], v[162:165], v[192:195], v[128:131]
	v_mfma_f32_16x16x32_bf16 v[124:127], v[184:187], v[192:195], v[124:127]
	v_mfma_f32_16x16x32_bf16 v[104:107], v[162:165], v[200:203], v[104:107]
	v_mfma_f32_16x16x32_bf16 v[100:103], v[184:187], v[200:203], v[100:103]
	v_mfma_f32_16x16x32_bf16 v[88:91], v[162:165], v[208:211], v[88:91]
	v_mfma_f32_16x16x32_bf16 v[84:87], v[184:187], v[208:211], v[84:87]
	v_mfma_f32_16x16x32_bf16 v[72:75], v[162:165], v[216:219], v[72:75]
	v_mfma_f32_16x16x32_bf16 v[68:71], v[184:187], v[216:219], v[68:71]
	v_mfma_f32_16x16x32_bf16 v[128:131], v[166:169], v[196:199], v[128:131]
	v_mfma_f32_16x16x32_bf16 v[124:127], v[188:191], v[196:199], v[124:127]
	v_mfma_f32_16x16x32_bf16 v[104:107], v[166:169], v[204:207], v[104:107]
	v_mfma_f32_16x16x32_bf16 v[100:103], v[188:191], v[204:207], v[100:103]
	v_mfma_f32_16x16x32_bf16 v[88:91], v[166:169], v[212:215], v[88:91]
	v_mfma_f32_16x16x32_bf16 v[84:87], v[188:191], v[212:215], v[84:87]
	v_mfma_f32_16x16x32_bf16 v[72:75], v[166:169], v[220:223], v[72:75]
	v_mfma_f32_16x16x32_bf16 v[68:71], v[188:191], v[220:223], v[68:71]
	s_barrier
	s_add_i32 s0, s60, s30
	v_lshl_add_u64 v[170:171], s[16:17], 0, v[174:175]
	s_mov_b32 m0, s0
	ds_read_b128 v[192:195], v161 offset:16384
	ds_read_b128 v[196:199], v161 offset:17408
	ds_read_b128 v[200:203], v161 offset:18432
	ds_read_b128 v[204:207], v161 offset:19456
	ds_read_b128 v[208:211], v161 offset:20480
	ds_read_b128 v[212:215], v161 offset:21504
	ds_read_b128 v[216:219], v161 offset:22528
	ds_read_b128 v[220:223], v161 offset:23552
	global_load_lds_dwordx4 v[170:171], off
	s_add_i32 m0, s0, 0x2000
	s_add_u32 s0, s16, 0x158000
	v_lshl_add_u64 v[224:225], s[16:17], 0, v[140:141]
	s_addc_u32 s1, s17, 0
	s_add_i32 s60, s61, s30
	global_load_lds_dwordx4 v[224:225], off
	v_lshl_add_u64 v[226:227], s[0:1], 0, v[174:175]
	s_mov_b32 m0, s60
	v_lshl_add_u64 v[228:229], s[18:19], 0, v[142:143]
	global_load_lds_dwordx4 v[226:227], off
	v_lshl_add_u64 v[226:227], s[0:1], 0, v[140:141]
	s_add_i32 m0, s60, 0x2000
	s_nop 0
	global_load_lds_dwordx4 v[226:227], off
	v_lshl_add_u64 v[226:227], s[18:19], 0, v[144:145]
	s_mov_b32 m0, s31
	s_nop 0
	global_load_lds_dwordx4 v[226:227], off
	s_mov_b32 m0, s34
	s_nop 0
	global_load_lds_dwordx4 v[228:229], off
	s_waitcnt vmcnt(8)
	s_waitcnt lgkmcnt(0)
	s_barrier
; #define PG8_STAGE(bufoff, gbase, voff) do { _Pragma("unroll") for (int _i = 0; _i < 2; ++_i) \
;         __builtin_amdgcn_global_load_lds((const unsigned*)((const char*)(gbase) + (voff)[_i]), (PG8_LAS unsigned*)(lds + (bufoff) + ldsw + _i * 8192), 16, 0, 0); } while (0)
; #define PG8_LDA(dst, b, h) do { _Pragma("unroll") for (int m = 0; m < 4; ++m) _Pragma("unroll") for (int k = 0; k < 2; ++k) dst[m][k] = *(const PG8_LAS bf16x8*)(lds + PG8_SA(b, h) + aoff + m * 2048 + k * 1024); } while (0)
; #define PG8_LDB(dst, b, h) do { _Pragma("unroll") for (int n = 0; n < 2; ++n) _Pragma("unroll") for (int k = 0; k < 2; ++k) dst[n][k] = *(const PG8_LAS bf16x8*)(lds + PG8_SB(b, h) + boff + n * 2048 + k * 1024); } while (0)
; #define PG8_MMA(ai, bj, At, Bt) do { __builtin_amdgcn_s_setprio(1); _Pragma("unroll") for (int m = 0; m < 4; ++m) _Pragma("unroll") for (int n = 0; n < 2; ++n) _Pragma("unroll") for (int k = 0; k < 2; ++k) \
;         acc[ai][bj][m][n] = __builtin_amdgcn_mfma_f32_16x16x32_bf16(Bt[n][k], At[m][k], acc[ai][bj][m][n], 0, 0, 0); __builtin_amdgcn_s_setprio(0); } while (0)
; #define PG8_WAIT_V(n) asm volatile("s_waitcnt vmcnt(" #n ")" ::: "memory")
; #define PG8_WAIT_L(n) asm volatile("s_waitcnt lgkmcnt(" #n ")" ::: "memory")
; #define PG8_BAR __builtin_amdgcn_s_barrier()
; #define PG8_SCHED __builtin_amdgcn_sched_barrier(0)
; template <class Epi, class Sched, bool ALIGN_EPI = false, bool SP2 = false>
; __device__ __forceinline__ void gemm_phase(PG8_LAS unsigned char* lds, const Gemm g, const Sched& S, const Epi& E) {
;     ...
;             PG8_LDA(At, 0, 1); PG8_STAGE(PG8_SB(0, 0), b2, voffB); PG8_STAGE(PG8_SB(0, 1), b2 + hstep, voffB); PG8_STAGE(PG8_SA(0, 0), a2, voffA);
;             PG8_WAIT_V(8); PG8_WAIT_L(0); PG8_BAR; PG8_MMA(1, 0, At, B0); PG8_MMA(1, 1, At, B1); PG8_BAR; PG8_SCHED;
;             PG8_LDB(B0, 1, 0); PG8_LDB(B1, 1, 1); PG8_SCHED; PG8_LDA(At, 1, 0); PG8_STAGE(PG8_SA(0, 1), a2 + hstep, voffA);
;             PG8_WAIT_V(8); PG8_WAIT_L(0); PG8_BAR; PG8_MMA(0, 0, At, B0); PG8_MMA(0, 1, At, B1); PG8_BAR; PG8_SCHED;
	v_mfma_f32_16x16x32_bf16 v[64:67], v[116:119], v[192:195], v[64:67]
	v_mfma_f32_16x16x32_bf16 v[60:63], v[150:153], v[192:195], v[60:63]
	v_mfma_f32_16x16x32_bf16 v[48:51], v[116:119], v[200:203], v[48:51]
	v_mfma_f32_16x16x32_bf16 v[44:47], v[150:153], v[200:203], v[44:47]
	v_mfma_f32_16x16x32_bf16 v[32:35], v[116:119], v[208:211], v[32:35]
	v_mfma_f32_16x16x32_bf16 v[28:31], v[150:153], v[208:211], v[28:31]
	v_mfma_f32_16x16x32_bf16 v[16:19], v[116:119], v[216:219], v[16:19]
	v_mfma_f32_16x16x32_bf16 v[12:15], v[150:153], v[216:219], v[12:15]
	v_mfma_f32_16x16x32_bf16 v[64:67], v[120:123], v[196:199], v[64:67]
	v_mfma_f32_16x16x32_bf16 v[60:63], v[154:157], v[196:199], v[60:63]
	v_mfma_f32_16x16x32_bf16 v[48:51], v[120:123], v[204:207], v[48:51]
	v_mfma_f32_16x16x32_bf16 v[44:47], v[154:157], v[204:207], v[44:47]
	v_mfma_f32_16x16x32_bf16 v[32:35], v[120:123], v[212:215], v[32:35]
	v_mfma_f32_16x16x32_bf16 v[28:31], v[154:157], v[212:215], v[28:31]
	v_mfma_f32_16x16x32_bf16 v[16:19], v[120:123], v[220:223], v[16:19]
	v_mfma_f32_16x16x32_bf16 v[12:15], v[154:157], v[220:223], v[12:15]
	v_mfma_f32_16x16x32_bf16 v[56:59], v[162:165], v[192:195], v[56:59]
	v_mfma_f32_16x16x32_bf16 v[52:55], v[184:187], v[192:195], v[52:55]
	v_mfma_f32_16x16x32_bf16 v[40:43], v[162:165], v[200:203], v[40:43]
	v_mfma_f32_16x16x32_bf16 v[36:39], v[184:187], v[200:203], v[36:39]
	v_mfma_f32_16x16x32_bf16 v[24:27], v[162:165], v[208:211], v[24:27]
	v_mfma_f32_16x16x32_bf16 v[20:23], v[184:187], v[208:211], v[20:23]
	v_mfma_f32_16x16x32_bf16 v[8:11], v[162:165], v[216:219], v[8:11]
	v_mfma_f32_16x16x32_bf16 v[4:7], v[184:187], v[216:219], v[4:7]
	v_mfma_f32_16x16x32_bf16 v[56:59], v[166:169], v[196:199], v[56:59]
	v_mfma_f32_16x16x32_bf16 v[52:55], v[188:191], v[196:199], v[52:55]
	v_mfma_f32_16x16x32_bf16 v[40:43], v[166:169], v[204:207], v[40:43]
	v_mfma_f32_16x16x32_bf16 v[36:39], v[188:191], v[204:207], v[36:39]
	v_mfma_f32_16x16x32_bf16 v[24:27], v[166:169], v[212:215], v[24:27]
	v_mfma_f32_16x16x32_bf16 v[20:23], v[188:191], v[212:215], v[20:23]
	v_mfma_f32_16x16x32_bf16 v[8:11], v[166:169], v[220:223], v[8:11]
	v_mfma_f32_16x16x32_bf16 v[4:7], v[188:191], v[220:223], v[4:7]
	s_barrier
	s_add_i32 s60, 0, 0x18000
	s_add_i32 s61, 0, 0x1c000
	v_add_u32_e32 v154, s60, v159
	v_add_u32_e32 v179, s61, v159
	ds_read_b128 v[116:119], v154
	ds_read_b128 v[120:123], v154 offset:1024
	ds_read_b128 v[150:153], v154 offset:2048
	ds_read_b128 v[154:157], v154 offset:3072
	ds_read_b128 v[162:165], v179
	ds_read_b128 v[166:169], v179 offset:1024
	ds_read_b128 v[184:187], v179 offset:2048
	ds_read_b128 v[188:191], v179 offset:3072
	s_add_u32 s0, s18, 0x158000
	s_addc_u32 s1, s19, 0
	s_mov_b32 m0, s35
	v_lshl_add_u64 v[230:231], s[0:1], 0, v[144:145]
	ds_read_b128 v[192:195], v161 offset:32768
	ds_read_b128 v[196:199], v161 offset:33792
	ds_read_b128 v[200:203], v161 offset:34816
	ds_read_b128 v[204:207], v161 offset:35840
	ds_read_b128 v[208:211], v161 offset:36864
	ds_read_b128 v[212:215], v161 offset:37888
	ds_read_b128 v[216:219], v161 offset:38912
	ds_read_b128 v[220:223], v161 offset:39936
	global_load_lds_dwordx4 v[230:231], off
	v_lshl_add_u64 v[230:231], s[0:1], 0, v[142:143]
	s_mov_b32 m0, s52
	s_nop 0
	global_load_lds_dwordx4 v[230:231], off
	s_waitcnt vmcnt(8)
	s_waitcnt lgkmcnt(0)
	s_barrier
	v_mfma_f32_16x16x32_bf16 v[136:139], v[116:119], v[192:195], v[136:139]
	v_mfma_f32_16x16x32_bf16 v[132:135], v[150:153], v[192:195], v[132:135]
	v_mfma_f32_16x16x32_bf16 v[112:115], v[116:119], v[200:203], v[112:115]
	v_mfma_f32_16x16x32_bf16 v[108:111], v[150:153], v[200:203], v[108:111]
	v_mfma_f32_16x16x32_bf16 v[96:99], v[116:119], v[208:211], v[96:99]
	v_mfma_f32_16x16x32_bf16 v[92:95], v[150:153], v[208:211], v[92:95]
	v_mfma_f32_16x16x32_bf16 v[80:83], v[116:119], v[216:219], v[80:83]
	v_mfma_f32_16x16x32_bf16 v[76:79], v[150:153], v[216:219], v[76:79]
	v_mfma_f32_16x16x32_bf16 v[136:139], v[120:123], v[196:199], v[136:139]
	v_mfma_f32_16x16x32_bf16 v[132:135], v[154:157], v[196:199], v[132:135]
	v_mfma_f32_16x16x32_bf16 v[112:115], v[120:123], v[204:207], v[112:115]
	v_mfma_f32_16x16x32_bf16 v[108:111], v[154:157], v[204:207], v[108:111]
	v_mfma_f32_16x16x32_bf16 v[96:99], v[120:123], v[212:215], v[96:99]
	v_mfma_f32_16x16x32_bf16 v[92:95], v[154:157], v[212:215], v[92:95]
	v_mfma_f32_16x16x32_bf16 v[80:83], v[120:123], v[220:223], v[80:83]
	v_mfma_f32_16x16x32_bf16 v[76:79], v[154:157], v[220:223], v[76:79]
	v_mfma_f32_16x16x32_bf16 v[128:131], v[162:165], v[192:195], v[128:131]
	v_mfma_f32_16x16x32_bf16 v[124:127], v[184:187], v[192:195], v[124:127]
	v_mfma_f32_16x16x32_bf16 v[104:107], v[162:165], v[200:203], v[104:107]
	v_mfma_f32_16x16x32_bf16 v[100:103], v[184:187], v[200:203], v[100:103]
	v_mfma_f32_16x16x32_bf16 v[88:91], v[162:165], v[208:211], v[88:91]
	v_mfma_f32_16x16x32_bf16 v[84:87], v[184:187], v[208:211], v[84:87]
	v_mfma_f32_16x16x32_bf16 v[72:75], v[162:165], v[216:219], v[72:75]
	v_mfma_f32_16x16x32_bf16 v[68:71], v[184:187], v[216:219], v[68:71]
	v_mfma_f32_16x16x32_bf16 v[128:131], v[166:169], v[196:199], v[128:131]
	v_mfma_f32_16x16x32_bf16 v[124:127], v[188:191], v[196:199], v[124:127]
	v_mfma_f32_16x16x32_bf16 v[104:107], v[166:169], v[204:207], v[104:107]
	v_mfma_f32_16x16x32_bf16 v[100:103], v[188:191], v[204:207], v[100:103]
	v_mfma_f32_16x16x32_bf16 v[88:91], v[166:169], v[212:215], v[88:91]
	v_mfma_f32_16x16x32_bf16 v[84:87], v[188:191], v[212:215], v[84:87]
	v_mfma_f32_16x16x32_bf16 v[72:75], v[166:169], v[220:223], v[72:75]
	v_mfma_f32_16x16x32_bf16 v[68:71], v[188:191], v[220:223], v[68:71]
	s_barrier
; #define PG8_STAGE(bufoff, gbase, voff) do { _Pragma("unroll") for (int _i = 0; _i < 2; ++_i) \
;         __builtin_amdgcn_global_load_lds((const unsigned*)((const char*)(gbase) + (voff)[_i]), (PG8_LAS unsigned*)(lds + (bufoff) + ldsw + _i * 8192), 16, 0, 0); } while (0)
; #define PG8_LDA(dst, b, h) do { _Pragma("unroll") for (int m = 0; m < 4; ++m) _Pragma("unroll") for (int k = 0; k < 2; ++k) dst[m][k] = *(const PG8_LAS bf16x8*)(lds + PG8_SA(b, h) + aoff + m * 2048 + k * 1024); } while (0)
; #define PG8_MMA(ai, bj, At, Bt) do { __builtin_amdgcn_s_setprio(1); _Pragma("unroll") for (int m = 0; m < 4; ++m) _Pragma("unroll") for (int n = 0; n < 2; ++n) _Pragma("unroll") for (int k = 0; k < 2; ++k) \
;         acc[ai][bj][m][n] = __builtin_amdgcn_mfma_f32_16x16x32_bf16(Bt[n][k], At[m][k], acc[ai][bj][m][n], 0, 0, 0); __builtin_amdgcn_s_setprio(0); } while (0)
; #define PG8_WAIT_V(n) asm volatile("s_waitcnt vmcnt(" #n ")" ::: "memory")
; #define PG8_WAIT_L(n) asm volatile("s_waitcnt lgkmcnt(" #n ")" ::: "memory")
; #define PG8_BAR __builtin_amdgcn_s_barrier()
; #define PG8_SCHED __builtin_amdgcn_sched_barrier(0)
; template <class Epi, class Sched, bool ALIGN_EPI = false, bool SP2 = false>
; __device__ __forceinline__ void gemm_phase(PG8_LAS unsigned char* lds, const Gemm g, const Sched& S, const Epi& E) {
;     ...
;             PG8_LDA(At, 1, 1); PG8_STAGE(PG8_SB(1, 0), b3, voffB); PG8_STAGE(PG8_SB(1, 1), b3 + hstep, voffB); PG8_STAGE(PG8_SA(1, 0), a3, voffA);
;             PG8_WAIT_V(8); PG8_WAIT_L(0); PG8_BAR; PG8_MMA(1, 0, At, B0); PG8_MMA(1, 1, At, B1); PG8_BAR; PG8_SCHED;
;     ...
;         if constexpr (ALIGN_EPI) { if (wr == 0) PG8_BAR; }
	s_add_i32 s0, s60, s30
	v_lshl_add_u64 v[170:171], v[170:171], 0, s[10:11]
	s_mov_b32 m0, s0
	ds_read_b128 v[192:195], v161 offset:49152
	ds_read_b128 v[196:199], v161 offset:50176
	ds_read_b128 v[200:203], v161 offset:51200
	ds_read_b128 v[204:207], v161 offset:52224
	ds_read_b128 v[208:211], v161 offset:53248
	ds_read_b128 v[212:215], v161 offset:54272
	ds_read_b128 v[216:219], v161 offset:55296
	ds_read_b128 v[220:223], v161 offset:56320
	global_load_lds_dwordx4 v[170:171], off
	s_add_i32 m0, s0, 0x2000
	s_add_u32 s0, s16, 0x158080
	v_lshl_add_u64 v[170:171], v[224:225], 0, s[10:11]
	s_addc_u32 s1, s17, 0
	s_add_i32 s16, s61, s30
	global_load_lds_dwordx4 v[170:171], off
	v_lshl_add_u64 v[170:171], s[0:1], 0, v[174:175]
	s_mov_b32 m0, s16
	s_nop 0
	global_load_lds_dwordx4 v[170:171], off
	v_lshl_add_u64 v[170:171], s[0:1], 0, v[140:141]
	s_add_i32 m0, s16, 0x2000
	s_nop 0
	global_load_lds_dwordx4 v[170:171], off
	v_lshl_add_u64 v[170:171], v[226:227], 0, s[10:11]
	s_mov_b32 m0, s54
	s_nop 0
	global_load_lds_dwordx4 v[170:171], off
	v_lshl_add_u64 v[170:171], v[228:229], 0, s[10:11]
	s_mov_b32 m0, s55
	s_nop 0
	global_load_lds_dwordx4 v[170:171], off
	s_waitcnt vmcnt(8)
	s_waitcnt lgkmcnt(0)
	s_barrier
	v_mfma_f32_16x16x32_bf16 v[64:67], v[116:119], v[192:195], v[64:67]
	v_mfma_f32_16x16x32_bf16 v[60:63], v[150:153], v[192:195], v[60:63]
	v_mfma_f32_16x16x32_bf16 v[48:51], v[116:119], v[200:203], v[48:51]
	v_mfma_f32_16x16x32_bf16 v[44:47], v[150:153], v[200:203], v[44:47]
	v_mfma_f32_16x16x32_bf16 v[32:35], v[116:119], v[208:211], v[32:35]
	v_mfma_f32_16x16x32_bf16 v[28:31], v[150:153], v[208:211], v[28:31]
	v_mfma_f32_16x16x32_bf16 v[16:19], v[116:119], v[216:219], v[16:19]
	v_mfma_f32_16x16x32_bf16 v[12:15], v[150:153], v[216:219], v[12:15]
	v_mfma_f32_16x16x32_bf16 v[64:67], v[120:123], v[196:199], v[64:67]
	v_mfma_f32_16x16x32_bf16 v[60:63], v[154:157], v[196:199], v[60:63]
	v_mfma_f32_16x16x32_bf16 v[48:51], v[120:123], v[204:207], v[48:51]
	v_mfma_f32_16x16x32_bf16 v[44:47], v[154:157], v[204:207], v[44:47]
	v_mfma_f32_16x16x32_bf16 v[32:35], v[120:123], v[212:215], v[32:35]
	v_mfma_f32_16x16x32_bf16 v[28:31], v[154:157], v[212:215], v[28:31]
	v_mfma_f32_16x16x32_bf16 v[16:19], v[120:123], v[220:223], v[16:19]
	v_mfma_f32_16x16x32_bf16 v[12:15], v[154:157], v[220:223], v[12:15]
	v_mfma_f32_16x16x32_bf16 v[56:59], v[162:165], v[192:195], v[56:59]
	v_mfma_f32_16x16x32_bf16 v[52:55], v[184:187], v[192:195], v[52:55]
	v_mfma_f32_16x16x32_bf16 v[40:43], v[162:165], v[200:203], v[40:43]
	v_mfma_f32_16x16x32_bf16 v[36:39], v[184:187], v[200:203], v[36:39]
	v_mfma_f32_16x16x32_bf16 v[24:27], v[162:165], v[208:211], v[24:27]
	v_mfma_f32_16x16x32_bf16 v[20:23], v[184:187], v[208:211], v[20:23]
	v_mfma_f32_16x16x32_bf16 v[8:11], v[162:165], v[216:219], v[8:11]
	v_mfma_f32_16x16x32_bf16 v[4:7], v[184:187], v[216:219], v[4:7]
	v_mfma_f32_16x16x32_bf16 v[56:59], v[166:169], v[196:199], v[56:59]
	v_mfma_f32_16x16x32_bf16 v[52:55], v[188:191], v[196:199], v[52:55]
	v_mfma_f32_16x16x32_bf16 v[40:43], v[166:169], v[204:207], v[40:43]
	v_mfma_f32_16x16x32_bf16 v[36:39], v[188:191], v[204:207], v[36:39]
	v_mfma_f32_16x16x32_bf16 v[24:27], v[166:169], v[212:215], v[24:27]
	v_mfma_f32_16x16x32_bf16 v[20:23], v[188:191], v[212:215], v[20:23]
	v_mfma_f32_16x16x32_bf16 v[8:11], v[166:169], v[220:223], v[8:11]
	v_mfma_f32_16x16x32_bf16 v[4:7], v[188:191], v[220:223], v[4:7]
	s_barrier
	s_add_i32 s25, s25, 2
	s_add_u32 s23, s23, 0x100
	s_addc_u32 s24, s24, 0
	s_cmpk_gt_u32 s25, 0x53
	s_mov_b64 s[0:1], s[14:15]
	s_cbranch_scc0 .LBB0_822
	s_and_b64 vcc, exec, s[48:49]
	s_cbranch_vccz .LBB0_825
	s_barrier
